# EpiWin sigmoid/silu classes: per-element -log2e multiplies and 1+e adds paired into v_pk_mul_f32 / v_pk_add_f32 (258 pairs)
# speedup vs baseline: 1.0060x; 1.0060x over previous
.LBB0_536:
	s_mov_b32 s98, 0xbfb8aa3b
	v_mov_b32_e32 v96, v189
	v_mov_b32_e32 v145, v188
	v_and_b32_e32 v171, 64, v225
	v_add_u32_e32 v96, s67, v96
	v_lshlrev_b32_e32 v144, 4, v145
	s_add_i32 s1, 0, 0x21000
	v_lshlrev_b32_e32 v146, 6, v96
	v_xor_b32_e32 v170, 16, v225
	v_add_u32_e32 v172, 64, v171
	s_waitcnt vmcnt(16)
	s_barrier
	v_add3_u32 v144, s1, v144, v146
	v_cmp_lt_i32_e32 vcc, v170, v172
	ds_read_b128 v[146:149], v144
	ds_read_b128 v[150:153], v144 offset:1024
	ds_read_b128 v[154:157], v144 offset:2048
	ds_read_b128 v[158:161], v144 offset:3072
	ds_read_b128 v[162:165], v144 offset:8192
	ds_read_b128 v[166:169], v144 offset:9216
	v_cndmask_b32_e32 v170, v225, v170, vcc
	v_lshlrev_b32_e32 v192, 2, v170
	s_waitcnt lgkmcnt(0)
	v_mov_b32_e32 v170, v147
	v_mov_b32_e32 v171, v148
	v_mov_b32_e32 v147, v149
	v_pk_add_f32 v[146:147], v[170:171], v[146:147]
	v_xor_b32_e32 v148, 32, v225
	v_add_f32_e32 v146, v146, v147
	ds_bpermute_b32 v147, v192, v146
	v_cmp_lt_i32_e32 vcc, v148, v172
	s_lshl_b32 s94, s93, 1
	v_readlane_b32 s1, v249, 47
	v_cndmask_b32_e32 v148, v225, v148, vcc
	v_lshlrev_b32_e32 v193, 2, v148
	s_waitcnt lgkmcnt(0)
	v_add_f32_e32 v170, v146, v147
	ds_bpermute_b32 v171, v193, v170
	v_add_f32_e32 v146, v150, v151
	v_add_f32_e32 v147, v152, v153
	v_add_f32_e32 v172, v146, v147
	ds_read_b128 v[146:149], v144 offset:10240
	ds_read_b128 v[150:153], v144 offset:11264
	s_waitcnt lgkmcnt(0)
	v_add_f32_e32 v144, v170, v171
	v_fmamk_f32 v144, v144, 0x3a800000, v226
	v_rsq_f32_e32 v170, v144
	v_add_f32_e32 v144, v154, v155
	v_add_f32_e32 v154, v156, v157
	v_add_f32_e32 v144, v144, v154
	ds_bpermute_b32 v154, v192, v144
	v_add_f32_e32 v155, v158, v159
	v_add_f32_e32 v156, v160, v161
	v_add_f32_e32 v157, v162, v163
	v_add_f32_e32 v158, v164, v165
	s_waitcnt lgkmcnt(0)
	v_add_f32_e32 v206, v144, v154
	v_add_f32_e32 v144, v166, v167
	v_add_f32_e32 v154, v168, v169
	v_add_f32_e32 v146, v146, v147
	v_add_f32_e32 v147, v148, v149
	v_add_f32_e32 v148, v150, v151
	v_add_f32_e32 v149, v152, v153
	v_add_f32_e32 v155, v155, v156
	v_add_f32_e32 v157, v157, v158
	v_add_f32_e32 v144, v144, v154
	v_add_f32_e32 v146, v146, v147
	v_add_f32_e32 v148, v148, v149
	ds_bpermute_b32 v173, v192, v172
	ds_bpermute_b32 v156, v192, v155
	ds_bpermute_b32 v158, v192, v157
	ds_bpermute_b32 v154, v192, v144
	ds_bpermute_b32 v147, v192, v146
	ds_bpermute_b32 v149, v192, v148
	s_waitcnt lgkmcnt(0)
	v_add_f32_e32 v208, v172, v173
	v_add_f32_e32 v204, v155, v156
	v_add_f32_e32 v202, v157, v158
	v_add_f32_e32 v200, v144, v154
	v_add_f32_e32 v198, v146, v147
	v_add_f32_e32 v196, v148, v149
	ds_bpermute_b32 v209, v193, v208
	ds_bpermute_b32 v207, v193, v206
	ds_bpermute_b32 v205, v193, v204
	ds_bpermute_b32 v203, v193, v202
	ds_bpermute_b32 v201, v193, v200
	ds_bpermute_b32 v199, v193, v198
	ds_bpermute_b32 v197, v193, v196
	v_lshl_add_u32 v148, s10, 8, v96
	v_lshlrev_b32_e32 v144, 3, v145
	v_ashrrev_i32_e32 v149, 31, v148
	s_cmp_gt_i32 s93, 2
	v_add_u32_e32 v146, s1, v144
	v_lshlrev_b64 v[152:153], 11, v[148:149]
	v_lshlrev_b64 v[156:157], 10, v[148:149]
	s_cselect_b64 s[12:13], -1, 0
	v_add_u32_e32 v195, 0xfffff300, v146
	v_ashrrev_i32_e32 v147, 31, v146
	v_add_u32_e32 v194, 0xfffffb00, v146
	v_cmp_eq_u32_e64 s[8:9], 0, v145
	v_lshl_add_u64 v[172:173], s[50:51], 0, v[152:153]
	v_lshl_add_u64 v[150:151], s[72:73], 0, v[156:157]
	v_lshl_add_u64 v[154:155], s[52:53], 0, v[152:153]
	v_lshl_add_u64 v[152:153], s[96:97], 0, v[156:157]
	v_pk_mul_f32 v[164:165], v[126:127], v[170:171] op_sel_hi:[1,0]
	v_pk_mul_f32 v[166:167], v[128:129], v[170:171] op_sel_hi:[1,0]
	v_pk_mul_f32 v[168:169], v[122:123], v[170:171] op_sel_hi:[1,0]
	v_pk_mul_f32 v[176:177], v[124:125], v[170:171] op_sel_hi:[1,0]
	s_mov_b64 s[10:11], -1
	s_and_b64 vcc, exec, s[12:13]
	s_cbranch_vccz .LBB0_558
	s_cmp_gt_u32 s94, 9
	s_cbranch_scc0 .LBB0_555
	s_cmp_gt_u32 s94, 13
	s_cbranch_scc0 .LBB0_552
	s_cmp_gt_u32 s94, 17
	s_cbranch_scc0 .LBB0_549
	s_cmp_gt_u32 s94, 21
	s_cbranch_scc0 .LBB0_546
	s_cmp_gt_u32 s94, 25
	s_cbranch_scc0 .LBB0_543
	v_pk_mul_f32 v[122:123], v[164:165], s[98:99] op_sel_hi:[1,0]
	v_pk_mul_f32 v[124:125], v[166:167], s[98:99] op_sel_hi:[1,0]
	v_mul_f32_e32 v127, 0xbfb8aa3b, v168
	v_mul_f32_e32 v128, 0xbfb8aa3b, v169
	v_exp_f32_e32 v122, v122
	v_exp_f32_e32 v123, v123
	v_exp_f32_e32 v124, v124
	v_exp_f32_e32 v125, v125
	v_exp_f32_e32 v127, v127
	v_exp_f32_e32 v128, v128
	v_mul_f32_e32 v129, 0xbfb8aa3b, v176
	v_mul_f32_e32 v156, 0xbfb8aa3b, v177
	v_exp_f32_e32 v129, v129
	v_exp_f32_e32 v156, v156
	v_pk_add_f32 v[122:123], v[122:123], 1.0 op_sel_hi:[1,0]
	v_pk_add_f32 v[124:125], v[124:125], 1.0 op_sel_hi:[1,0]
	v_add_f32_e32 v127, 1.0, v127
	v_pk_add_f32 v[128:129], v[128:129], 1.0 op_sel_hi:[1,0]
	v_rcp_f32_e32 v122, v122
	v_rcp_f32_e32 v123, v123
	v_rcp_f32_e32 v124, v124
	v_rcp_f32_e32 v125, v125
	v_rcp_f32_e32 v127, v127
	v_rcp_f32_e32 v128, v128
	v_lshl_add_u32 v96, s93, 8, v195
	v_add_f32_e32 v156, 1.0, v156
	v_ashrrev_i32_e32 v126, 10, v96
	v_rcp_f32_e32 v129, v129
	v_rcp_f32_e32 v156, v156
	v_cvt_pk_bf16_f32 v122, v122, v123
	v_cvt_pk_bf16_f32 v123, v124, v125
	v_cvt_pk_bf16_f32 v124, v127, v128
	v_ashrrev_i32_e32 v127, 31, v126
	v_and_b32_e32 v96, 0x3f8, v96
	v_lshlrev_b64 v[126:127], 25, v[126:127]
	v_lshl_add_u64 v[126:127], v[172:173], 0, v[126:127]
	v_lshlrev_b32_e32 v96, 1, v96
	v_cvt_pk_bf16_f32 v125, v129, v156
	v_lshl_add_u64 v[126:127], v[126:127], 0, v[96:97]
	global_store_dwordx4 v[126:127], v[122:125], off
	s_mov_b64 s[10:11], 0
	s_mov_b64 s[10:11], 0
	s_branch .LBB0_558

.LBB0_567:
	v_lshlrev_b32_e32 v122, 2, v145
	v_ashrrev_i32_e32 v123, 31, v122
	v_readlane_b32 s10, v249, 62
	v_lshlrev_b64 v[122:123], 2, v[122:123]
	v_readlane_b32 s11, v249, 63
	s_or_b32 s95, s94, 1
	v_mov_b32_e32 v171, v170
	v_lshl_add_u64 v[124:125], s[10:11], 0, v[122:123]
	v_readlane_b32 s10, v248, 0
	v_readlane_b32 s11, v248, 1
	s_cmp_gt_i32 s95, 4
	v_ashrrev_i32_e32 v145, 31, v144
	v_lshl_add_u64 v[122:123], s[10:11], 0, v[122:123]
	v_pk_mul_f32 v[164:165], v[118:119], v[170:171]
	v_pk_mul_f32 v[166:167], v[120:121], v[170:171]
	v_pk_mul_f32 v[168:169], v[114:115], v[170:171]
	v_pk_mul_f32 v[170:171], v[116:117], v[170:171]
	s_cselect_b64 s[14:15], -1, 0
	s_cmp_lt_i32 s95, 5
	s_mov_b64 s[10:11], -1
	s_cbranch_scc1 .LBB0_594
	s_cmp_eq_u32 s93, 2
	s_cbranch_scc1 .LBB0_590
	s_cmp_lt_u32 s94, 10
	s_cbranch_scc1 .LBB0_587
	s_cmp_lt_u32 s94, 14
	s_cbranch_scc1 .LBB0_584
	s_cmp_lt_u32 s94, 18
	s_cbranch_scc1 .LBB0_581
	s_cmp_lt_u32 s94, 22
	s_cbranch_scc1 .LBB0_578
	s_cmp_lt_u32 s94, 26
	s_cbranch_scc1 .LBB0_575
	v_pk_mul_f32 v[114:115], v[164:165], s[98:99] op_sel_hi:[1,0]
	v_pk_mul_f32 v[116:117], v[166:167], s[98:99] op_sel_hi:[1,0]
	v_mul_f32_e32 v119, 0xbfb8aa3b, v168
	v_mul_f32_e32 v120, 0xbfb8aa3b, v169
	v_exp_f32_e32 v114, v114
	v_exp_f32_e32 v115, v115
	v_exp_f32_e32 v116, v116
	v_exp_f32_e32 v117, v117
	v_exp_f32_e32 v119, v119
	v_exp_f32_e32 v120, v120
	v_mul_f32_e32 v121, 0xbfb8aa3b, v170
	v_mul_f32_e32 v149, 0xbfb8aa3b, v171
	v_exp_f32_e32 v121, v121
	v_exp_f32_e32 v149, v149
	v_pk_add_f32 v[114:115], v[114:115], 1.0 op_sel_hi:[1,0]
	v_pk_add_f32 v[116:117], v[116:117], 1.0 op_sel_hi:[1,0]
	v_add_f32_e32 v119, 1.0, v119
	v_pk_add_f32 v[120:121], v[120:121], 1.0 op_sel_hi:[1,0]
	v_rcp_f32_e32 v114, v114
	v_rcp_f32_e32 v115, v115
	v_rcp_f32_e32 v116, v116
	v_rcp_f32_e32 v117, v117
	v_rcp_f32_e32 v119, v119
	v_rcp_f32_e32 v120, v120
	v_lshl_add_u32 v96, s95, 7, v195
	v_add_f32_e32 v149, 1.0, v149
	v_ashrrev_i32_e32 v118, 10, v96
	v_rcp_f32_e32 v121, v121
	v_rcp_f32_e32 v149, v149
	v_cvt_pk_bf16_f32 v114, v114, v115
	v_cvt_pk_bf16_f32 v115, v116, v117
	v_cvt_pk_bf16_f32 v116, v119, v120
	v_ashrrev_i32_e32 v119, 31, v118
	v_and_b32_e32 v96, 0x3f8, v96
	v_lshlrev_b64 v[118:119], 25, v[118:119]
	v_lshl_add_u64 v[118:119], v[172:173], 0, v[118:119]
	v_lshlrev_b32_e32 v96, 1, v96
	v_cvt_pk_bf16_f32 v117, v121, v149
	v_lshl_add_u64 v[118:119], v[118:119], 0, v[96:97]
	s_mov_b64 s[10:11], 0
	global_store_dwordx4 v[118:119], v[114:117], off
	s_mov_b64 s[10:11], 0
	s_branch .LBB0_603

.LBB0_603:
	s_waitcnt lgkmcnt(0)
	v_add_f32_e32 v96, v208, v209
	v_fmamk_f32 v96, v96, 0x3a800000, v226
	v_rsq_f32_e32 v156, v96
	v_add_u32_e32 v114, 16, v148
	v_ashrrev_i32_e32 v115, 31, v114
	v_lshlrev_b64 v[118:119], 11, v[114:115]
	v_lshlrev_b64 v[150:151], 10, v[114:115]
	v_cndmask_b32_e64 v96, 0, 1, s[12:13]
	v_lshl_add_u64 v[158:159], s[50:51], 0, v[118:119]
	v_lshl_add_u64 v[116:117], s[72:73], 0, v[150:151]
	v_lshl_add_u64 v[120:121], s[52:53], 0, v[118:119]
	v_lshl_add_u64 v[118:119], s[96:97], 0, v[150:151]
	v_pk_mul_f32 v[154:155], v[110:111], v[156:157] op_sel_hi:[1,0]
	v_pk_mul_f32 v[162:163], v[112:113], v[156:157] op_sel_hi:[1,0]
	v_pk_mul_f32 v[164:165], v[106:107], v[156:157] op_sel_hi:[1,0]
	v_pk_mul_f32 v[166:167], v[108:109], v[156:157] op_sel_hi:[1,0]
	v_cmp_ne_u32_e64 s[10:11], 1, v96
	s_andn2_b64 vcc, exec, s[12:13]
	s_mov_b64 s[12:13], -1
	s_cbranch_vccnz .LBB0_625
	s_cmp_lt_u32 s94, 10
	s_cbranch_scc1 .LBB0_622
	s_cmp_lt_u32 s94, 14
	s_cbranch_scc1 .LBB0_619
	s_cmp_lt_u32 s94, 18
	s_cbranch_scc1 .LBB0_616
	s_cmp_lt_u32 s94, 22
	s_cbranch_scc1 .LBB0_613
	s_cmp_lt_u32 s94, 26
	s_cbranch_scc1 .LBB0_610
	v_pk_mul_f32 v[106:107], v[154:155], s[98:99] op_sel_hi:[1,0]
	v_pk_mul_f32 v[108:109], v[162:163], s[98:99] op_sel_hi:[1,0]
	v_mul_f32_e32 v111, 0xbfb8aa3b, v164
	v_mul_f32_e32 v112, 0xbfb8aa3b, v165
	v_exp_f32_e32 v106, v106
	v_exp_f32_e32 v107, v107
	v_exp_f32_e32 v108, v108
	v_exp_f32_e32 v109, v109
	v_exp_f32_e32 v111, v111
	v_exp_f32_e32 v112, v112
	v_mul_f32_e32 v113, 0xbfb8aa3b, v166
	v_mul_f32_e32 v149, 0xbfb8aa3b, v167
	v_exp_f32_e32 v113, v113
	v_exp_f32_e32 v149, v149
	v_pk_add_f32 v[106:107], v[106:107], 1.0 op_sel_hi:[1,0]
	v_pk_add_f32 v[108:109], v[108:109], 1.0 op_sel_hi:[1,0]
	v_add_f32_e32 v111, 1.0, v111
	v_pk_add_f32 v[112:113], v[112:113], 1.0 op_sel_hi:[1,0]
	v_rcp_f32_e32 v106, v106
	v_rcp_f32_e32 v107, v107
	v_rcp_f32_e32 v108, v108
	v_rcp_f32_e32 v109, v109
	v_rcp_f32_e32 v111, v111
	v_rcp_f32_e32 v112, v112
	v_lshl_add_u32 v96, s93, 8, v195
	v_add_f32_e32 v149, 1.0, v149
	v_ashrrev_i32_e32 v110, 10, v96
	v_rcp_f32_e32 v113, v113
	v_rcp_f32_e32 v149, v149
	v_cvt_pk_bf16_f32 v106, v106, v107
	v_cvt_pk_bf16_f32 v107, v108, v109
	v_cvt_pk_bf16_f32 v108, v111, v112
	v_ashrrev_i32_e32 v111, 31, v110
	v_and_b32_e32 v96, 0x3f8, v96
	v_lshlrev_b64 v[110:111], 25, v[110:111]
	v_lshl_add_u64 v[110:111], v[158:159], 0, v[110:111]
	v_lshlrev_b32_e32 v96, 1, v96
	v_cvt_pk_bf16_f32 v109, v113, v149
	v_lshl_add_u64 v[110:111], v[110:111], 0, v[96:97]
	s_mov_b64 s[12:13], 0
	global_store_dwordx4 v[110:111], v[106:109], off
	s_mov_b64 s[12:13], 0
	s_branch .LBB0_625

.LBB0_634:
	v_mov_b32_e32 v157, v156
	v_cndmask_b32_e64 v96, 0, 1, s[14:15]
	v_pk_mul_f32 v[106:107], v[102:103], v[156:157]
	v_pk_mul_f32 v[108:109], v[104:105], v[156:157]
	v_pk_mul_f32 v[154:155], v[98:99], v[156:157]
	v_pk_mul_f32 v[156:157], v[100:101], v[156:157]
	v_cmp_ne_u32_e64 s[12:13], 1, v96
	s_andn2_b64 vcc, exec, s[14:15]
	s_mov_b64 s[14:15], -1
	s_cbranch_vccnz .LBB0_661
	s_cmp_eq_u32 s93, 2
	s_cbranch_scc1 .LBB0_657
	s_cmp_lt_u32 s94, 10
	s_cbranch_scc1 .LBB0_654
	s_cmp_lt_u32 s94, 14
	s_cbranch_scc1 .LBB0_651
	s_cmp_lt_u32 s94, 18
	s_cbranch_scc1 .LBB0_648
	s_cmp_lt_u32 s94, 22
	s_cbranch_scc1 .LBB0_645
	s_cmp_lt_u32 s94, 26
	s_cbranch_scc1 .LBB0_642
	v_pk_mul_f32 v[98:99], v[106:107], s[98:99] op_sel_hi:[1,0]
	v_pk_mul_f32 v[100:101], v[108:109], s[98:99] op_sel_hi:[1,0]
	v_mul_f32_e32 v103, 0xbfb8aa3b, v154
	v_mul_f32_e32 v104, 0xbfb8aa3b, v155
	v_exp_f32_e32 v98, v98
	v_exp_f32_e32 v99, v99
	v_exp_f32_e32 v100, v100
	v_exp_f32_e32 v101, v101
	v_exp_f32_e32 v103, v103
	v_exp_f32_e32 v104, v104
	v_mul_f32_e32 v105, 0xbfb8aa3b, v156
	v_mul_f32_e32 v115, 0xbfb8aa3b, v157
	v_exp_f32_e32 v105, v105
	v_exp_f32_e32 v115, v115
	v_pk_add_f32 v[98:99], v[98:99], 1.0 op_sel_hi:[1,0]
	v_pk_add_f32 v[100:101], v[100:101], 1.0 op_sel_hi:[1,0]
	v_add_f32_e32 v103, 1.0, v103
	v_pk_add_f32 v[104:105], v[104:105], 1.0 op_sel_hi:[1,0]
	v_rcp_f32_e32 v98, v98
	v_rcp_f32_e32 v99, v99
	v_rcp_f32_e32 v100, v100
	v_rcp_f32_e32 v101, v101
	v_rcp_f32_e32 v103, v103
	v_rcp_f32_e32 v104, v104
	v_lshl_add_u32 v96, s95, 7, v195
	v_add_f32_e32 v115, 1.0, v115
	v_ashrrev_i32_e32 v102, 10, v96
	v_rcp_f32_e32 v105, v105
	v_rcp_f32_e32 v115, v115
	v_cvt_pk_bf16_f32 v98, v98, v99
	v_cvt_pk_bf16_f32 v99, v100, v101
	v_cvt_pk_bf16_f32 v100, v103, v104
	v_ashrrev_i32_e32 v103, 31, v102
	v_and_b32_e32 v96, 0x3f8, v96
	v_lshlrev_b64 v[102:103], 25, v[102:103]
	v_lshl_add_u64 v[102:103], v[158:159], 0, v[102:103]
	v_lshlrev_b32_e32 v96, 1, v96
	v_cvt_pk_bf16_f32 v101, v105, v115
	v_lshl_add_u64 v[102:103], v[102:103], 0, v[96:97]
	s_mov_b64 s[14:15], 0
	global_store_dwordx4 v[102:103], v[98:101], off
	s_mov_b64 s[14:15], 0
	s_branch .LBB0_670

.LBB0_670:
	v_add_f32_e32 v96, v206, v207
	v_fmamk_f32 v96, v96, 0x3a800000, v226
	v_rsq_f32_e32 v112, v96
	v_add_u32_e32 v98, 32, v148
	v_ashrrev_i32_e32 v99, 31, v98
	v_lshlrev_b64 v[102:103], 11, v[98:99]
	v_lshlrev_b64 v[106:107], 10, v[98:99]
	v_lshl_add_u64 v[114:115], s[50:51], 0, v[102:103]
	v_lshl_add_u64 v[100:101], s[72:73], 0, v[106:107]
	v_lshl_add_u64 v[104:105], s[52:53], 0, v[102:103]
	v_lshl_add_u64 v[102:103], s[96:97], 0, v[106:107]
	v_pk_mul_f32 v[110:111], v[92:93], v[112:113] op_sel_hi:[1,0]
	v_pk_mul_f32 v[118:119], v[94:95], v[112:113] op_sel_hi:[1,0]
	v_pk_mul_f32 v[120:121], v[88:89], v[112:113] op_sel_hi:[1,0]
	v_pk_mul_f32 v[150:151], v[90:91], v[112:113] op_sel_hi:[1,0]
	s_and_b64 vcc, exec, s[10:11]
	s_mov_b64 s[14:15], -1
	s_cbranch_vccnz .LBB0_692
	s_cmp_lt_u32 s94, 10
	s_cbranch_scc1 .LBB0_689
	s_cmp_lt_u32 s94, 14
	s_cbranch_scc1 .LBB0_686
	s_cmp_lt_u32 s94, 18
	s_cbranch_scc1 .LBB0_683
	s_cmp_lt_u32 s94, 22
	s_cbranch_scc1 .LBB0_680
	s_cmp_lt_u32 s94, 26
	s_cbranch_scc1 .LBB0_677
	v_mul_f32_e32 v89, 0xbfb8aa3b, v110
	v_mul_f32_e32 v90, 0xbfb8aa3b, v111
	v_mul_f32_e32 v91, 0xbfb8aa3b, v118
	v_mul_f32_e32 v93, 0xbfb8aa3b, v119
	v_exp_f32_e32 v89, v89
	v_exp_f32_e32 v90, v90
	v_exp_f32_e32 v91, v91
	v_exp_f32_e32 v93, v93
	v_mul_f32_e32 v96, 0xbfb8aa3b, v150
	v_mul_f32_e32 v106, 0xbfb8aa3b, v151
	v_pk_mul_f32 v[94:95], v[120:121], s[98:99] op_sel_hi:[1,0]
	v_exp_f32_e32 v96, v96
	v_exp_f32_e32 v106, v106
	v_exp_f32_e32 v94, v94
	v_exp_f32_e32 v95, v95
	v_add_f32_e32 v89, 1.0, v89
	v_pk_add_f32 v[90:91], v[90:91], 1.0 op_sel_hi:[1,0]
	v_add_f32_e32 v93, 1.0, v93
	v_rcp_f32_e32 v89, v89
	v_rcp_f32_e32 v90, v90
	v_rcp_f32_e32 v91, v91
	v_rcp_f32_e32 v93, v93
	v_add_f32_e32 v96, 1.0, v96
	v_add_f32_e32 v106, 1.0, v106
	v_lshl_add_u32 v88, s93, 8, v195
	v_pk_add_f32 v[94:95], v[94:95], 1.0 op_sel_hi:[1,0]
	v_rcp_f32_e32 v96, v96
	v_rcp_f32_e32 v106, v106
	v_ashrrev_i32_e32 v92, 10, v88
	v_rcp_f32_e32 v94, v94
	v_rcp_f32_e32 v95, v95
	v_and_b32_e32 v107, 0x3f8, v88
	v_cvt_pk_bf16_f32 v88, v89, v90
	v_cvt_pk_bf16_f32 v89, v91, v93
	v_ashrrev_i32_e32 v93, 31, v92
	v_lshlrev_b64 v[92:93], 25, v[92:93]
	v_cvt_pk_bf16_f32 v91, v96, v106
	v_lshl_add_u64 v[92:93], v[114:115], 0, v[92:93]
	v_lshlrev_b32_e32 v96, 1, v107
	v_cvt_pk_bf16_f32 v90, v94, v95
	v_lshl_add_u64 v[92:93], v[92:93], 0, v[96:97]
	s_mov_b64 s[14:15], 0
	global_store_dwordx4 v[92:93], v[88:91], off
	s_mov_b64 s[14:15], 0
	s_branch .LBB0_692

.LBB0_680:
	s_andn2_b64 vcc, exec, s[14:15]
	s_cbranch_vccnz .LBB0_682
	v_pk_mul_f32 v[88:89], v[110:111], s[98:99] op_sel_hi:[1,0]
	v_pk_mul_f32 v[90:91], v[118:119], s[98:99] op_sel_hi:[1,0]
	v_pk_mul_f32 v[92:93], v[120:121], s[98:99] op_sel_hi:[1,0]
	v_exp_f32_e32 v88, v88
	v_exp_f32_e32 v89, v89
	v_exp_f32_e32 v90, v90
	v_exp_f32_e32 v91, v91
	v_exp_f32_e32 v92, v92
	v_exp_f32_e32 v93, v93
	v_pk_mul_f32 v[94:95], v[150:151], s[98:99] op_sel_hi:[1,0]
	v_exp_f32_e32 v94, v94
	v_exp_f32_e32 v95, v95
	v_pk_add_f32 v[88:89], v[88:89], 1.0 op_sel_hi:[1,0]
	v_pk_add_f32 v[90:91], v[90:91], 1.0 op_sel_hi:[1,0]
	v_pk_add_f32 v[92:93], v[92:93], 1.0 op_sel_hi:[1,0]
	v_rcp_f32_e32 v88, v88
	v_rcp_f32_e32 v89, v89
	v_rcp_f32_e32 v90, v90
	v_rcp_f32_e32 v91, v91
	v_rcp_f32_e32 v92, v92
	v_rcp_f32_e32 v93, v93
	v_pk_add_f32 v[94:95], v[94:95], 1.0 op_sel_hi:[1,0]
	v_rcp_f32_e32 v94, v94
	v_rcp_f32_e32 v95, v95
	v_pk_mul_f32 v[88:89], v[110:111], v[88:89]
	v_pk_mul_f32 v[90:91], v[118:119], v[90:91]
	v_pk_mul_f32 v[92:93], v[120:121], v[92:93]
	s_lshl_b32 s48, s93, 8
	v_cvt_pk_bf16_f32 v88, v88, v89
	v_cvt_pk_bf16_f32 v89, v90, v91
	v_cvt_pk_bf16_f32 v90, v92, v93
	v_lshl_add_u64 v[92:93], s[48:49], 1, v[100:101]
	v_lshl_add_u64 v[92:93], v[146:147], 1, v[92:93]
	v_pk_mul_f32 v[94:95], v[150:151], v[94:95]
	v_add_co_u32_e32 v92, vcc, 0xd11e000, v92
	v_cvt_pk_bf16_f32 v91, v94, v95
	s_nop 0
	v_addc_co_u32_e32 v93, vcc, 0, v93, vcc
	global_store_dwordx4 v[92:93], v[88:91], off offset:3584
	s_mov_b64 s[14:15], 0
	s_branch .LBB0_692

.LBB0_689:
	s_andn2_b64 vcc, exec, s[14:15]
	s_cbranch_vccnz .LBB0_691
	v_pk_mul_f32 v[88:89], v[110:111], s[98:99] op_sel_hi:[1,0]
	v_pk_mul_f32 v[90:91], v[118:119], s[98:99] op_sel_hi:[1,0]
	v_pk_mul_f32 v[92:93], v[120:121], s[98:99] op_sel_hi:[1,0]
	v_exp_f32_e32 v88, v88
	v_exp_f32_e32 v89, v89
	v_exp_f32_e32 v90, v90
	v_exp_f32_e32 v91, v91
	v_exp_f32_e32 v92, v92
	v_exp_f32_e32 v93, v93
	v_pk_mul_f32 v[94:95], v[150:151], s[98:99] op_sel_hi:[1,0]
	v_exp_f32_e32 v94, v94
	v_exp_f32_e32 v95, v95
	v_pk_add_f32 v[88:89], v[88:89], 1.0 op_sel_hi:[1,0]
	v_pk_add_f32 v[90:91], v[90:91], 1.0 op_sel_hi:[1,0]
	v_pk_add_f32 v[92:93], v[92:93], 1.0 op_sel_hi:[1,0]
	v_rcp_f32_e32 v88, v88
	v_rcp_f32_e32 v89, v89
	v_rcp_f32_e32 v90, v90
	v_rcp_f32_e32 v91, v91
	v_rcp_f32_e32 v92, v92
	v_rcp_f32_e32 v93, v93
	v_pk_add_f32 v[94:95], v[94:95], 1.0 op_sel_hi:[1,0]
	v_rcp_f32_e32 v94, v94
	v_rcp_f32_e32 v95, v95
	v_pk_mul_f32 v[88:89], v[110:111], v[88:89]
	v_pk_mul_f32 v[90:91], v[118:119], v[90:91]
	v_pk_mul_f32 v[92:93], v[120:121], v[92:93]
	s_lshl_b32 s48, s93, 8
	v_cvt_pk_bf16_f32 v88, v88, v89
	v_cvt_pk_bf16_f32 v89, v90, v91
	v_cvt_pk_bf16_f32 v90, v92, v93
	v_lshl_add_u64 v[92:93], s[48:49], 1, v[100:101]
	v_lshl_add_u64 v[92:93], v[146:147], 1, v[92:93]
	v_pk_mul_f32 v[94:95], v[150:151], v[94:95]
	v_add_co_u32_e32 v92, vcc, 0x811f000, v92
	v_cvt_pk_bf16_f32 v91, v94, v95
	s_nop 0
	v_addc_co_u32_e32 v93, vcc, 0, v93, vcc
	global_store_dwordx4 v[92:93], v[88:91], off offset:2560

.LBB0_701:
	v_mov_b32_e32 v113, v112
	v_pk_mul_f32 v[88:89], v[84:85], v[112:113]
	v_pk_mul_f32 v[90:91], v[86:87], v[112:113]
	v_pk_mul_f32 v[110:111], v[80:81], v[112:113]
	v_pk_mul_f32 v[112:113], v[82:83], v[112:113]
	s_and_b64 vcc, exec, s[12:13]
	s_mov_b64 s[14:15], -1
	s_cbranch_vccnz .LBB0_728
	s_cmp_eq_u32 s93, 2
	s_cbranch_scc1 .LBB0_724
	s_cmp_lt_u32 s94, 10
	s_cbranch_scc1 .LBB0_721
	s_cmp_lt_u32 s94, 14
	s_cbranch_scc1 .LBB0_718
	s_cmp_lt_u32 s94, 18
	s_cbranch_scc1 .LBB0_715
	s_cmp_lt_u32 s94, 22
	s_cbranch_scc1 .LBB0_712
	s_cmp_lt_u32 s94, 26
	s_cbranch_scc1 .LBB0_709
	v_mul_f32_e32 v81, 0xbfb8aa3b, v88
	v_mul_f32_e32 v82, 0xbfb8aa3b, v89
	v_mul_f32_e32 v83, 0xbfb8aa3b, v90
	v_mul_f32_e32 v85, 0xbfb8aa3b, v91
	v_exp_f32_e32 v81, v81
	v_exp_f32_e32 v82, v82
	v_exp_f32_e32 v83, v83
	v_exp_f32_e32 v85, v85
	v_mul_f32_e32 v96, 0xbfb8aa3b, v112
	v_mul_f32_e32 v99, 0xbfb8aa3b, v113
	v_pk_mul_f32 v[86:87], v[110:111], s[98:99] op_sel_hi:[1,0]
	v_exp_f32_e32 v96, v96
	v_exp_f32_e32 v99, v99
	v_exp_f32_e32 v86, v86
	v_exp_f32_e32 v87, v87
	v_add_f32_e32 v81, 1.0, v81
	v_pk_add_f32 v[82:83], v[82:83], 1.0 op_sel_hi:[1,0]
	v_add_f32_e32 v85, 1.0, v85
	v_rcp_f32_e32 v81, v81
	v_rcp_f32_e32 v82, v82
	v_rcp_f32_e32 v83, v83
	v_rcp_f32_e32 v85, v85
	v_add_f32_e32 v96, 1.0, v96
	v_add_f32_e32 v99, 1.0, v99
	v_lshl_add_u32 v80, s95, 7, v195
	v_pk_add_f32 v[86:87], v[86:87], 1.0 op_sel_hi:[1,0]
	v_rcp_f32_e32 v96, v96
	v_rcp_f32_e32 v99, v99
	v_ashrrev_i32_e32 v84, 10, v80
	v_rcp_f32_e32 v86, v86
	v_rcp_f32_e32 v87, v87
	v_and_b32_e32 v118, 0x3f8, v80
	v_cvt_pk_bf16_f32 v80, v81, v82
	v_cvt_pk_bf16_f32 v81, v83, v85
	v_ashrrev_i32_e32 v85, 31, v84
	v_lshlrev_b64 v[84:85], 25, v[84:85]
	v_cvt_pk_bf16_f32 v83, v96, v99
	v_lshl_add_u64 v[84:85], v[114:115], 0, v[84:85]
	v_lshlrev_b32_e32 v96, 1, v118
	v_cvt_pk_bf16_f32 v82, v86, v87
	v_lshl_add_u64 v[84:85], v[84:85], 0, v[96:97]
	s_mov_b64 s[14:15], 0
	global_store_dwordx4 v[84:85], v[80:83], off
	s_mov_b64 s[14:15], 0
	s_branch .LBB0_737

.LBB0_712:
	s_andn2_b64 vcc, exec, s[14:15]
	s_cbranch_vccnz .LBB0_714
	v_pk_mul_f32 v[80:81], v[88:89], s[98:99] op_sel_hi:[1,0]
	v_pk_mul_f32 v[82:83], v[90:91], s[98:99] op_sel_hi:[1,0]
	v_pk_mul_f32 v[84:85], v[110:111], s[98:99] op_sel_hi:[1,0]
	v_exp_f32_e32 v80, v80
	v_exp_f32_e32 v81, v81
	v_exp_f32_e32 v82, v82
	v_exp_f32_e32 v83, v83
	v_exp_f32_e32 v84, v84
	v_exp_f32_e32 v85, v85
	v_pk_mul_f32 v[86:87], v[112:113], s[98:99] op_sel_hi:[1,0]
	v_exp_f32_e32 v86, v86
	v_exp_f32_e32 v87, v87
	v_pk_add_f32 v[80:81], v[80:81], 1.0 op_sel_hi:[1,0]
	v_pk_add_f32 v[82:83], v[82:83], 1.0 op_sel_hi:[1,0]
	v_pk_add_f32 v[84:85], v[84:85], 1.0 op_sel_hi:[1,0]
	v_rcp_f32_e32 v80, v80
	v_rcp_f32_e32 v81, v81
	v_rcp_f32_e32 v82, v82
	v_rcp_f32_e32 v83, v83
	v_rcp_f32_e32 v84, v84
	v_rcp_f32_e32 v85, v85
	v_pk_add_f32 v[86:87], v[86:87], 1.0 op_sel_hi:[1,0]
	v_rcp_f32_e32 v86, v86
	v_rcp_f32_e32 v87, v87
	v_pk_mul_f32 v[80:81], v[88:89], v[80:81]
	v_pk_mul_f32 v[82:83], v[90:91], v[82:83]
	v_pk_mul_f32 v[84:85], v[110:111], v[84:85]
	s_lshl_b32 s48, s95, 8
	v_cvt_pk_bf16_f32 v80, v80, v81
	v_cvt_pk_bf16_f32 v81, v82, v83
	v_cvt_pk_bf16_f32 v82, v84, v85
	v_lshl_add_u64 v[84:85], v[100:101], 0, s[48:49]
	v_lshl_add_u64 v[84:85], v[146:147], 1, v[84:85]
	v_pk_mul_f32 v[86:87], v[112:113], v[86:87]
	v_add_co_u32_e32 v84, vcc, 0xd11e000, v84
	v_cvt_pk_bf16_f32 v83, v86, v87
	s_nop 0
	v_addc_co_u32_e32 v85, vcc, 0, v85, vcc
	global_store_dwordx4 v[84:85], v[80:83], off offset:3584
	s_mov_b64 s[14:15], 0
	s_branch .LBB0_737

.LBB0_721:
	s_andn2_b64 vcc, exec, s[14:15]
	s_cbranch_vccnz .LBB0_723
	v_pk_mul_f32 v[80:81], v[88:89], s[98:99] op_sel_hi:[1,0]
	v_pk_mul_f32 v[82:83], v[90:91], s[98:99] op_sel_hi:[1,0]
	v_pk_mul_f32 v[84:85], v[110:111], s[98:99] op_sel_hi:[1,0]
	v_exp_f32_e32 v80, v80
	v_exp_f32_e32 v81, v81
	v_exp_f32_e32 v82, v82
	v_exp_f32_e32 v83, v83
	v_exp_f32_e32 v84, v84
	v_exp_f32_e32 v85, v85
	v_pk_mul_f32 v[86:87], v[112:113], s[98:99] op_sel_hi:[1,0]
	v_exp_f32_e32 v86, v86
	v_exp_f32_e32 v87, v87
	v_pk_add_f32 v[80:81], v[80:81], 1.0 op_sel_hi:[1,0]
	v_pk_add_f32 v[82:83], v[82:83], 1.0 op_sel_hi:[1,0]
	v_pk_add_f32 v[84:85], v[84:85], 1.0 op_sel_hi:[1,0]
	v_rcp_f32_e32 v80, v80
	v_rcp_f32_e32 v81, v81
	v_rcp_f32_e32 v82, v82
	v_rcp_f32_e32 v83, v83
	v_rcp_f32_e32 v84, v84
	v_rcp_f32_e32 v85, v85
	v_pk_add_f32 v[86:87], v[86:87], 1.0 op_sel_hi:[1,0]
	v_rcp_f32_e32 v86, v86
	v_rcp_f32_e32 v87, v87
	v_pk_mul_f32 v[80:81], v[88:89], v[80:81]
	v_pk_mul_f32 v[82:83], v[90:91], v[82:83]
	v_pk_mul_f32 v[84:85], v[110:111], v[84:85]
	s_lshl_b32 s48, s95, 8
	v_cvt_pk_bf16_f32 v80, v80, v81
	v_cvt_pk_bf16_f32 v81, v82, v83
	v_cvt_pk_bf16_f32 v82, v84, v85
	v_lshl_add_u64 v[84:85], v[100:101], 0, s[48:49]
	v_lshl_add_u64 v[84:85], v[146:147], 1, v[84:85]
	v_pk_mul_f32 v[86:87], v[112:113], v[86:87]
	v_add_co_u32_e32 v84, vcc, 0x811f000, v84
	v_cvt_pk_bf16_f32 v83, v86, v87
	s_nop 0
	v_addc_co_u32_e32 v85, vcc, 0, v85, vcc
	global_store_dwordx4 v[84:85], v[80:83], off offset:2560
	s_mov_b64 s[14:15], 0
	s_branch .LBB0_737

.LBB0_737:
	v_add_f32_e32 v80, v204, v205
	v_fmamk_f32 v80, v80, 0x3a800000, v226
	v_rsq_f32_e32 v94, v80
	v_add_u32_e32 v80, 48, v148
	v_ashrrev_i32_e32 v81, 31, v80
	v_lshlrev_b64 v[84:85], 11, v[80:81]
	v_lshlrev_b64 v[88:89], 10, v[80:81]
	v_lshl_add_u64 v[98:99], s[50:51], 0, v[84:85]
	v_lshl_add_u64 v[82:83], s[72:73], 0, v[88:89]
	v_lshl_add_u64 v[86:87], s[52:53], 0, v[84:85]
	v_lshl_add_u64 v[84:85], s[96:97], 0, v[88:89]
	v_pk_mul_f32 v[92:93], v[76:77], v[94:95] op_sel_hi:[1,0]
	v_pk_mul_f32 v[102:103], v[78:79], v[94:95] op_sel_hi:[1,0]
	v_pk_mul_f32 v[104:105], v[72:73], v[94:95] op_sel_hi:[1,0]
	v_pk_mul_f32 v[106:107], v[74:75], v[94:95] op_sel_hi:[1,0]
	s_and_b64 vcc, exec, s[10:11]
	s_mov_b64 s[14:15], -1
	s_cbranch_vccnz .LBB0_759
	s_cmp_lt_u32 s94, 10
	s_cbranch_scc1 .LBB0_756
	s_cmp_lt_u32 s94, 14
	s_cbranch_scc1 .LBB0_753
	s_cmp_lt_u32 s94, 18
	s_cbranch_scc1 .LBB0_750
	s_cmp_lt_u32 s94, 22
	s_cbranch_scc1 .LBB0_747
	s_cmp_lt_u32 s94, 26
	s_cbranch_scc1 .LBB0_744
	v_mul_f32_e32 v73, 0xbfb8aa3b, v92
	v_mul_f32_e32 v74, 0xbfb8aa3b, v93
	v_mul_f32_e32 v75, 0xbfb8aa3b, v102
	v_mul_f32_e32 v77, 0xbfb8aa3b, v103
	v_exp_f32_e32 v73, v73
	v_exp_f32_e32 v74, v74
	v_exp_f32_e32 v75, v75
	v_exp_f32_e32 v77, v77
	v_pk_mul_f32 v[78:79], v[104:105], s[98:99] op_sel_hi:[1,0]
	v_pk_mul_f32 v[88:89], v[106:107], s[98:99] op_sel_hi:[1,0]
	v_exp_f32_e32 v78, v78
	v_exp_f32_e32 v79, v79
	v_exp_f32_e32 v88, v88
	v_exp_f32_e32 v89, v89
	v_add_f32_e32 v73, 1.0, v73
	v_pk_add_f32 v[74:75], v[74:75], 1.0 op_sel_hi:[1,0]
	v_add_f32_e32 v77, 1.0, v77
	v_rcp_f32_e32 v73, v73
	v_rcp_f32_e32 v74, v74
	v_rcp_f32_e32 v75, v75
	v_rcp_f32_e32 v77, v77
	v_lshl_add_u32 v72, s93, 8, v195
	v_pk_add_f32 v[78:79], v[78:79], 1.0 op_sel_hi:[1,0]
	v_pk_add_f32 v[88:89], v[88:89], 1.0 op_sel_hi:[1,0]
	v_ashrrev_i32_e32 v76, 10, v72
	v_rcp_f32_e32 v78, v78
	v_rcp_f32_e32 v79, v79
	v_rcp_f32_e32 v88, v88
	v_rcp_f32_e32 v89, v89
	v_and_b32_e32 v90, 0x3f8, v72
	v_cvt_pk_bf16_f32 v72, v73, v74
	v_cvt_pk_bf16_f32 v73, v75, v77
	v_ashrrev_i32_e32 v77, 31, v76
	v_lshlrev_b64 v[76:77], 25, v[76:77]
	v_lshl_add_u64 v[76:77], v[98:99], 0, v[76:77]
	v_lshlrev_b32_e32 v96, 1, v90
	v_cvt_pk_bf16_f32 v74, v78, v79
	v_cvt_pk_bf16_f32 v75, v88, v89
	v_lshl_add_u64 v[76:77], v[76:77], 0, v[96:97]
	s_mov_b64 s[14:15], 0
	global_store_dwordx4 v[76:77], v[72:75], off
	s_mov_b64 s[14:15], 0
	s_branch .LBB0_759

.LBB0_747:
	s_andn2_b64 vcc, exec, s[14:15]
	s_cbranch_vccnz .LBB0_749
	v_pk_mul_f32 v[72:73], v[92:93], s[98:99] op_sel_hi:[1,0]
	v_pk_mul_f32 v[74:75], v[102:103], s[98:99] op_sel_hi:[1,0]
	v_pk_mul_f32 v[76:77], v[104:105], s[98:99] op_sel_hi:[1,0]
	v_exp_f32_e32 v72, v72
	v_exp_f32_e32 v73, v73
	v_exp_f32_e32 v74, v74
	v_exp_f32_e32 v75, v75
	v_exp_f32_e32 v76, v76
	v_exp_f32_e32 v77, v77
	v_pk_mul_f32 v[78:79], v[106:107], s[98:99] op_sel_hi:[1,0]
	v_exp_f32_e32 v78, v78
	v_exp_f32_e32 v79, v79
	v_pk_add_f32 v[72:73], v[72:73], 1.0 op_sel_hi:[1,0]
	v_pk_add_f32 v[74:75], v[74:75], 1.0 op_sel_hi:[1,0]
	v_pk_add_f32 v[76:77], v[76:77], 1.0 op_sel_hi:[1,0]
	v_rcp_f32_e32 v72, v72
	v_rcp_f32_e32 v73, v73
	v_rcp_f32_e32 v74, v74
	v_rcp_f32_e32 v75, v75
	v_rcp_f32_e32 v76, v76
	v_rcp_f32_e32 v77, v77
	v_pk_add_f32 v[78:79], v[78:79], 1.0 op_sel_hi:[1,0]
	v_rcp_f32_e32 v78, v78
	v_rcp_f32_e32 v79, v79
	v_pk_mul_f32 v[72:73], v[92:93], v[72:73]
	v_pk_mul_f32 v[74:75], v[102:103], v[74:75]
	v_pk_mul_f32 v[76:77], v[104:105], v[76:77]
	s_lshl_b32 s48, s93, 8
	v_cvt_pk_bf16_f32 v72, v72, v73
	v_cvt_pk_bf16_f32 v73, v74, v75
	v_cvt_pk_bf16_f32 v74, v76, v77
	v_lshl_add_u64 v[76:77], s[48:49], 1, v[82:83]
	v_lshl_add_u64 v[76:77], v[146:147], 1, v[76:77]
	v_pk_mul_f32 v[78:79], v[106:107], v[78:79]
	v_add_co_u32_e32 v76, vcc, 0xd11e000, v76
	v_cvt_pk_bf16_f32 v75, v78, v79
	s_nop 0
	v_addc_co_u32_e32 v77, vcc, 0, v77, vcc
	global_store_dwordx4 v[76:77], v[72:75], off offset:3584
	s_mov_b64 s[14:15], 0
	s_branch .LBB0_759

.LBB0_756:
	s_andn2_b64 vcc, exec, s[14:15]
	s_cbranch_vccnz .LBB0_758
	v_pk_mul_f32 v[72:73], v[92:93], s[98:99] op_sel_hi:[1,0]
	v_pk_mul_f32 v[74:75], v[102:103], s[98:99] op_sel_hi:[1,0]
	v_pk_mul_f32 v[76:77], v[104:105], s[98:99] op_sel_hi:[1,0]
	v_exp_f32_e32 v72, v72
	v_exp_f32_e32 v73, v73
	v_exp_f32_e32 v74, v74
	v_exp_f32_e32 v75, v75
	v_exp_f32_e32 v76, v76
	v_exp_f32_e32 v77, v77
	v_pk_mul_f32 v[78:79], v[106:107], s[98:99] op_sel_hi:[1,0]
	v_exp_f32_e32 v78, v78
	v_exp_f32_e32 v79, v79
	v_pk_add_f32 v[72:73], v[72:73], 1.0 op_sel_hi:[1,0]
	v_pk_add_f32 v[74:75], v[74:75], 1.0 op_sel_hi:[1,0]
	v_pk_add_f32 v[76:77], v[76:77], 1.0 op_sel_hi:[1,0]
	v_rcp_f32_e32 v72, v72
	v_rcp_f32_e32 v73, v73
	v_rcp_f32_e32 v74, v74
	v_rcp_f32_e32 v75, v75
	v_rcp_f32_e32 v76, v76
	v_rcp_f32_e32 v77, v77
	v_pk_add_f32 v[78:79], v[78:79], 1.0 op_sel_hi:[1,0]
	v_rcp_f32_e32 v78, v78
	v_rcp_f32_e32 v79, v79
	v_pk_mul_f32 v[72:73], v[92:93], v[72:73]
	v_pk_mul_f32 v[74:75], v[102:103], v[74:75]
	v_pk_mul_f32 v[76:77], v[104:105], v[76:77]
	s_lshl_b32 s48, s93, 8
	v_cvt_pk_bf16_f32 v72, v72, v73
	v_cvt_pk_bf16_f32 v73, v74, v75
	v_cvt_pk_bf16_f32 v74, v76, v77
	v_lshl_add_u64 v[76:77], s[48:49], 1, v[82:83]
	v_lshl_add_u64 v[76:77], v[146:147], 1, v[76:77]
	v_pk_mul_f32 v[78:79], v[106:107], v[78:79]
	v_add_co_u32_e32 v76, vcc, 0x811f000, v76
	v_cvt_pk_bf16_f32 v75, v78, v79
	s_nop 0
	v_addc_co_u32_e32 v77, vcc, 0, v77, vcc
	global_store_dwordx4 v[76:77], v[72:75], off offset:2560

.LBB0_768:
	v_mov_b32_e32 v95, v94
	v_pk_mul_f32 v[72:73], v[68:69], v[94:95]
	v_pk_mul_f32 v[74:75], v[70:71], v[94:95]
	v_pk_mul_f32 v[92:93], v[64:65], v[94:95]
	v_pk_mul_f32 v[94:95], v[66:67], v[94:95]
	s_and_b64 vcc, exec, s[12:13]
	s_mov_b64 s[14:15], -1
	s_cbranch_vccnz .LBB0_795
	s_cmp_eq_u32 s93, 2
	s_cbranch_scc1 .LBB0_791
	s_cmp_lt_u32 s94, 10
	s_cbranch_scc1 .LBB0_788
	s_cmp_lt_u32 s94, 14
	s_cbranch_scc1 .LBB0_785
	s_cmp_lt_u32 s94, 18
	s_cbranch_scc1 .LBB0_782
	s_cmp_lt_u32 s94, 22
	s_cbranch_scc1 .LBB0_779
	s_cmp_lt_u32 s94, 26
	s_cbranch_scc1 .LBB0_776
	v_mul_f32_e32 v65, 0xbfb8aa3b, v72
	v_mul_f32_e32 v66, 0xbfb8aa3b, v73
	v_mul_f32_e32 v67, 0xbfb8aa3b, v74
	v_mul_f32_e32 v69, 0xbfb8aa3b, v75
	v_exp_f32_e32 v65, v65
	v_exp_f32_e32 v66, v66
	v_exp_f32_e32 v67, v67
	v_exp_f32_e32 v69, v69
	v_mul_f32_e32 v81, 0xbfb8aa3b, v94
	v_mul_f32_e32 v96, 0xbfb8aa3b, v95
	v_pk_mul_f32 v[70:71], v[92:93], s[98:99] op_sel_hi:[1,0]
	v_exp_f32_e32 v81, v81
	v_exp_f32_e32 v96, v96
	v_exp_f32_e32 v70, v70
	v_exp_f32_e32 v71, v71
	v_add_f32_e32 v65, 1.0, v65
	v_pk_add_f32 v[66:67], v[66:67], 1.0 op_sel_hi:[1,0]
	v_add_f32_e32 v69, 1.0, v69
	v_rcp_f32_e32 v65, v65
	v_rcp_f32_e32 v66, v66
	v_rcp_f32_e32 v67, v67
	v_rcp_f32_e32 v69, v69
	v_add_f32_e32 v81, 1.0, v81
	v_add_f32_e32 v96, 1.0, v96
	v_lshl_add_u32 v64, s95, 7, v195
	v_pk_add_f32 v[70:71], v[70:71], 1.0 op_sel_hi:[1,0]
	v_rcp_f32_e32 v81, v81
	v_rcp_f32_e32 v96, v96
	v_ashrrev_i32_e32 v68, 10, v64
	v_rcp_f32_e32 v70, v70
	v_rcp_f32_e32 v71, v71
	v_and_b32_e32 v102, 0x3f8, v64
	v_cvt_pk_bf16_f32 v64, v65, v66
	v_cvt_pk_bf16_f32 v65, v67, v69
	v_ashrrev_i32_e32 v69, 31, v68
	v_lshlrev_b64 v[68:69], 25, v[68:69]
	v_cvt_pk_bf16_f32 v67, v81, v96
	v_lshl_add_u64 v[68:69], v[98:99], 0, v[68:69]
	v_lshlrev_b32_e32 v96, 1, v102
	v_cvt_pk_bf16_f32 v66, v70, v71
	v_lshl_add_u64 v[68:69], v[68:69], 0, v[96:97]
	s_mov_b64 s[14:15], 0
	global_store_dwordx4 v[68:69], v[64:67], off
	s_mov_b64 s[14:15], 0
	s_branch .LBB0_804

.LBB0_779:
	s_andn2_b64 vcc, exec, s[14:15]
	s_cbranch_vccnz .LBB0_781
	v_pk_mul_f32 v[64:65], v[72:73], s[98:99] op_sel_hi:[1,0]
	v_pk_mul_f32 v[66:67], v[74:75], s[98:99] op_sel_hi:[1,0]
	v_pk_mul_f32 v[68:69], v[92:93], s[98:99] op_sel_hi:[1,0]
	v_exp_f32_e32 v64, v64
	v_exp_f32_e32 v65, v65
	v_exp_f32_e32 v66, v66
	v_exp_f32_e32 v67, v67
	v_exp_f32_e32 v68, v68
	v_exp_f32_e32 v69, v69
	v_pk_mul_f32 v[70:71], v[94:95], s[98:99] op_sel_hi:[1,0]
	v_exp_f32_e32 v70, v70
	v_exp_f32_e32 v71, v71
	v_pk_add_f32 v[64:65], v[64:65], 1.0 op_sel_hi:[1,0]
	v_pk_add_f32 v[66:67], v[66:67], 1.0 op_sel_hi:[1,0]
	v_pk_add_f32 v[68:69], v[68:69], 1.0 op_sel_hi:[1,0]
	v_rcp_f32_e32 v64, v64
	v_rcp_f32_e32 v65, v65
	v_rcp_f32_e32 v66, v66
	v_rcp_f32_e32 v67, v67
	v_rcp_f32_e32 v68, v68
	v_rcp_f32_e32 v69, v69
	v_pk_add_f32 v[70:71], v[70:71], 1.0 op_sel_hi:[1,0]
	v_rcp_f32_e32 v70, v70
	v_rcp_f32_e32 v71, v71
	v_pk_mul_f32 v[64:65], v[72:73], v[64:65]
	v_pk_mul_f32 v[66:67], v[74:75], v[66:67]
	v_pk_mul_f32 v[68:69], v[92:93], v[68:69]
	s_lshl_b32 s48, s95, 8
	v_cvt_pk_bf16_f32 v64, v64, v65
	v_cvt_pk_bf16_f32 v65, v66, v67
	v_cvt_pk_bf16_f32 v66, v68, v69
	v_lshl_add_u64 v[68:69], v[82:83], 0, s[48:49]
	v_lshl_add_u64 v[68:69], v[146:147], 1, v[68:69]
	v_pk_mul_f32 v[70:71], v[94:95], v[70:71]
	v_add_co_u32_e32 v68, vcc, 0xd11e000, v68
	v_cvt_pk_bf16_f32 v67, v70, v71
	s_nop 0
	v_addc_co_u32_e32 v69, vcc, 0, v69, vcc
	global_store_dwordx4 v[68:69], v[64:67], off offset:3584
	s_mov_b64 s[14:15], 0
	s_branch .LBB0_804

.LBB0_788:
	s_andn2_b64 vcc, exec, s[14:15]
	s_cbranch_vccnz .LBB0_790
	v_pk_mul_f32 v[64:65], v[72:73], s[98:99] op_sel_hi:[1,0]
	v_pk_mul_f32 v[66:67], v[74:75], s[98:99] op_sel_hi:[1,0]
	v_pk_mul_f32 v[68:69], v[92:93], s[98:99] op_sel_hi:[1,0]
	v_exp_f32_e32 v64, v64
	v_exp_f32_e32 v65, v65
	v_exp_f32_e32 v66, v66
	v_exp_f32_e32 v67, v67
	v_exp_f32_e32 v68, v68
	v_exp_f32_e32 v69, v69
	v_pk_mul_f32 v[70:71], v[94:95], s[98:99] op_sel_hi:[1,0]
	v_exp_f32_e32 v70, v70
	v_exp_f32_e32 v71, v71
	v_pk_add_f32 v[64:65], v[64:65], 1.0 op_sel_hi:[1,0]
	v_pk_add_f32 v[66:67], v[66:67], 1.0 op_sel_hi:[1,0]
	v_pk_add_f32 v[68:69], v[68:69], 1.0 op_sel_hi:[1,0]
	v_rcp_f32_e32 v64, v64
	v_rcp_f32_e32 v65, v65
	v_rcp_f32_e32 v66, v66
	v_rcp_f32_e32 v67, v67
	v_rcp_f32_e32 v68, v68
	v_rcp_f32_e32 v69, v69
	v_pk_add_f32 v[70:71], v[70:71], 1.0 op_sel_hi:[1,0]
	v_rcp_f32_e32 v70, v70
	v_rcp_f32_e32 v71, v71
	v_pk_mul_f32 v[64:65], v[72:73], v[64:65]
	v_pk_mul_f32 v[66:67], v[74:75], v[66:67]
	v_pk_mul_f32 v[68:69], v[92:93], v[68:69]
	s_lshl_b32 s48, s95, 8
	v_cvt_pk_bf16_f32 v64, v64, v65
	v_cvt_pk_bf16_f32 v65, v66, v67
	v_cvt_pk_bf16_f32 v66, v68, v69
	v_lshl_add_u64 v[68:69], v[82:83], 0, s[48:49]
	v_lshl_add_u64 v[68:69], v[146:147], 1, v[68:69]
	v_pk_mul_f32 v[70:71], v[94:95], v[70:71]
	v_add_co_u32_e32 v68, vcc, 0x811f000, v68
	v_cvt_pk_bf16_f32 v67, v70, v71
	s_nop 0
	v_addc_co_u32_e32 v69, vcc, 0, v69, vcc
	global_store_dwordx4 v[68:69], v[64:67], off offset:2560
	s_mov_b64 s[14:15], 0
	s_branch .LBB0_804

.LBB0_804:
	v_add_f32_e32 v64, v202, v203
	v_fmamk_f32 v64, v64, 0x3a800000, v226
	v_rsq_f32_e32 v78, v64
	v_add_u32_e32 v64, 0x80, v148
	v_ashrrev_i32_e32 v65, 31, v64
	v_lshlrev_b64 v[68:69], 11, v[64:65]
	v_lshlrev_b64 v[72:73], 10, v[64:65]
	v_lshl_add_u64 v[80:81], s[50:51], 0, v[68:69]
	v_lshl_add_u64 v[66:67], s[72:73], 0, v[72:73]
	v_lshl_add_u64 v[70:71], s[52:53], 0, v[68:69]
	v_lshl_add_u64 v[68:69], s[96:97], 0, v[72:73]
	v_pk_mul_f32 v[76:77], v[60:61], v[78:79] op_sel_hi:[1,0]
	v_pk_mul_f32 v[84:85], v[62:63], v[78:79] op_sel_hi:[1,0]
	v_pk_mul_f32 v[86:87], v[56:57], v[78:79] op_sel_hi:[1,0]
	v_pk_mul_f32 v[88:89], v[58:59], v[78:79] op_sel_hi:[1,0]
	s_and_b64 vcc, exec, s[10:11]
	s_mov_b64 s[14:15], -1
	s_cbranch_vccnz .LBB0_826
	s_cmp_lt_u32 s94, 10
	s_cbranch_scc1 .LBB0_823
	s_cmp_lt_u32 s94, 14
	s_cbranch_scc1 .LBB0_820
	s_cmp_lt_u32 s94, 18
	s_cbranch_scc1 .LBB0_817
	s_cmp_lt_u32 s94, 22
	s_cbranch_scc1 .LBB0_814
	s_cmp_lt_u32 s94, 26
	s_cbranch_scc1 .LBB0_811
	v_mul_f32_e32 v57, 0xbfb8aa3b, v76
	v_mul_f32_e32 v58, 0xbfb8aa3b, v77
	v_mul_f32_e32 v59, 0xbfb8aa3b, v84
	v_mul_f32_e32 v61, 0xbfb8aa3b, v85
	v_exp_f32_e32 v57, v57
	v_exp_f32_e32 v58, v58
	v_exp_f32_e32 v59, v59
	v_exp_f32_e32 v61, v61
	v_pk_mul_f32 v[62:63], v[86:87], s[98:99] op_sel_hi:[1,0]
	v_pk_mul_f32 v[72:73], v[88:89], s[98:99] op_sel_hi:[1,0]
	v_exp_f32_e32 v62, v62
	v_exp_f32_e32 v63, v63
	v_exp_f32_e32 v72, v72
	v_exp_f32_e32 v73, v73
	v_add_f32_e32 v57, 1.0, v57
	v_pk_add_f32 v[58:59], v[58:59], 1.0 op_sel_hi:[1,0]
	v_add_f32_e32 v61, 1.0, v61
	v_rcp_f32_e32 v57, v57
	v_rcp_f32_e32 v58, v58
	v_rcp_f32_e32 v59, v59
	v_rcp_f32_e32 v61, v61
	v_lshl_add_u32 v56, s93, 8, v195
	v_pk_add_f32 v[62:63], v[62:63], 1.0 op_sel_hi:[1,0]
	v_pk_add_f32 v[72:73], v[72:73], 1.0 op_sel_hi:[1,0]
	v_ashrrev_i32_e32 v60, 10, v56
	v_rcp_f32_e32 v62, v62
	v_rcp_f32_e32 v63, v63
	v_rcp_f32_e32 v72, v72
	v_rcp_f32_e32 v73, v73
	v_and_b32_e32 v74, 0x3f8, v56
	v_cvt_pk_bf16_f32 v56, v57, v58
	v_cvt_pk_bf16_f32 v57, v59, v61
	v_ashrrev_i32_e32 v61, 31, v60
	v_lshlrev_b64 v[60:61], 25, v[60:61]
	v_lshl_add_u64 v[60:61], v[80:81], 0, v[60:61]
	v_lshlrev_b32_e32 v96, 1, v74
	v_cvt_pk_bf16_f32 v58, v62, v63
	v_cvt_pk_bf16_f32 v59, v72, v73
	v_lshl_add_u64 v[60:61], v[60:61], 0, v[96:97]
	s_mov_b64 s[14:15], 0
	global_store_dwordx4 v[60:61], v[56:59], off
	s_mov_b64 s[14:15], 0
	s_branch .LBB0_826

.LBB0_814:
	s_andn2_b64 vcc, exec, s[14:15]
	s_cbranch_vccnz .LBB0_816
	v_pk_mul_f32 v[56:57], v[76:77], s[98:99] op_sel_hi:[1,0]
	v_pk_mul_f32 v[58:59], v[84:85], s[98:99] op_sel_hi:[1,0]
	v_pk_mul_f32 v[60:61], v[86:87], s[98:99] op_sel_hi:[1,0]
	v_exp_f32_e32 v56, v56
	v_exp_f32_e32 v57, v57
	v_exp_f32_e32 v58, v58
	v_exp_f32_e32 v59, v59
	v_exp_f32_e32 v60, v60
	v_exp_f32_e32 v61, v61
	v_pk_mul_f32 v[62:63], v[88:89], s[98:99] op_sel_hi:[1,0]
	v_exp_f32_e32 v62, v62
	v_exp_f32_e32 v63, v63
	v_pk_add_f32 v[56:57], v[56:57], 1.0 op_sel_hi:[1,0]
	v_pk_add_f32 v[58:59], v[58:59], 1.0 op_sel_hi:[1,0]
	v_pk_add_f32 v[60:61], v[60:61], 1.0 op_sel_hi:[1,0]
	v_rcp_f32_e32 v56, v56
	v_rcp_f32_e32 v57, v57
	v_rcp_f32_e32 v58, v58
	v_rcp_f32_e32 v59, v59
	v_rcp_f32_e32 v60, v60
	v_rcp_f32_e32 v61, v61
	v_pk_add_f32 v[62:63], v[62:63], 1.0 op_sel_hi:[1,0]
	v_rcp_f32_e32 v62, v62
	v_rcp_f32_e32 v63, v63
	v_pk_mul_f32 v[56:57], v[76:77], v[56:57]
	v_pk_mul_f32 v[58:59], v[84:85], v[58:59]
	v_pk_mul_f32 v[60:61], v[86:87], v[60:61]
	s_lshl_b32 s48, s93, 8
	v_cvt_pk_bf16_f32 v56, v56, v57
	v_cvt_pk_bf16_f32 v57, v58, v59
	v_cvt_pk_bf16_f32 v58, v60, v61
	v_lshl_add_u64 v[60:61], s[48:49], 1, v[66:67]
	v_lshl_add_u64 v[60:61], v[146:147], 1, v[60:61]
	v_pk_mul_f32 v[62:63], v[88:89], v[62:63]
	v_add_co_u32_e32 v60, vcc, 0xd11e000, v60
	v_cvt_pk_bf16_f32 v59, v62, v63
	s_nop 0
	v_addc_co_u32_e32 v61, vcc, 0, v61, vcc
	global_store_dwordx4 v[60:61], v[56:59], off offset:3584
	s_mov_b64 s[14:15], 0
	s_branch .LBB0_826

.LBB0_823:
	s_andn2_b64 vcc, exec, s[14:15]
	s_cbranch_vccnz .LBB0_825
	v_pk_mul_f32 v[56:57], v[76:77], s[98:99] op_sel_hi:[1,0]
	v_pk_mul_f32 v[58:59], v[84:85], s[98:99] op_sel_hi:[1,0]
	v_pk_mul_f32 v[60:61], v[86:87], s[98:99] op_sel_hi:[1,0]
	v_exp_f32_e32 v56, v56
	v_exp_f32_e32 v57, v57
	v_exp_f32_e32 v58, v58
	v_exp_f32_e32 v59, v59
	v_exp_f32_e32 v60, v60
	v_exp_f32_e32 v61, v61
	v_pk_mul_f32 v[62:63], v[88:89], s[98:99] op_sel_hi:[1,0]
	v_exp_f32_e32 v62, v62
	v_exp_f32_e32 v63, v63
	v_pk_add_f32 v[56:57], v[56:57], 1.0 op_sel_hi:[1,0]
	v_pk_add_f32 v[58:59], v[58:59], 1.0 op_sel_hi:[1,0]
	v_pk_add_f32 v[60:61], v[60:61], 1.0 op_sel_hi:[1,0]
	v_rcp_f32_e32 v56, v56
	v_rcp_f32_e32 v57, v57
	v_rcp_f32_e32 v58, v58
	v_rcp_f32_e32 v59, v59
	v_rcp_f32_e32 v60, v60
	v_rcp_f32_e32 v61, v61
	v_pk_add_f32 v[62:63], v[62:63], 1.0 op_sel_hi:[1,0]
	v_rcp_f32_e32 v62, v62
	v_rcp_f32_e32 v63, v63
	v_pk_mul_f32 v[56:57], v[76:77], v[56:57]
	v_pk_mul_f32 v[58:59], v[84:85], v[58:59]
	v_pk_mul_f32 v[60:61], v[86:87], v[60:61]
	s_lshl_b32 s48, s93, 8
	v_cvt_pk_bf16_f32 v56, v56, v57
	v_cvt_pk_bf16_f32 v57, v58, v59
	v_cvt_pk_bf16_f32 v58, v60, v61
	v_lshl_add_u64 v[60:61], s[48:49], 1, v[66:67]
	v_lshl_add_u64 v[60:61], v[146:147], 1, v[60:61]
	v_pk_mul_f32 v[62:63], v[88:89], v[62:63]
	v_add_co_u32_e32 v60, vcc, 0x811f000, v60
	v_cvt_pk_bf16_f32 v59, v62, v63
	s_nop 0
	v_addc_co_u32_e32 v61, vcc, 0, v61, vcc
	global_store_dwordx4 v[60:61], v[56:59], off offset:2560

.LBB0_835:
	v_mov_b32_e32 v79, v78
	v_pk_mul_f32 v[56:57], v[52:53], v[78:79]
	v_pk_mul_f32 v[58:59], v[54:55], v[78:79]
	v_pk_mul_f32 v[76:77], v[48:49], v[78:79]
	v_pk_mul_f32 v[78:79], v[50:51], v[78:79]
	s_and_b64 vcc, exec, s[12:13]
	s_mov_b64 s[14:15], -1
	s_cbranch_vccnz .LBB0_862
	s_cmp_eq_u32 s93, 2
	s_cbranch_scc1 .LBB0_858
	s_cmp_lt_u32 s94, 10
	s_cbranch_scc1 .LBB0_855
	s_cmp_lt_u32 s94, 14
	s_cbranch_scc1 .LBB0_852
	s_cmp_lt_u32 s94, 18
	s_cbranch_scc1 .LBB0_849
	s_cmp_lt_u32 s94, 22
	s_cbranch_scc1 .LBB0_846
	s_cmp_lt_u32 s94, 26
	s_cbranch_scc1 .LBB0_843
	v_mul_f32_e32 v49, 0xbfb8aa3b, v56
	v_mul_f32_e32 v50, 0xbfb8aa3b, v57
	v_mul_f32_e32 v51, 0xbfb8aa3b, v58
	v_mul_f32_e32 v53, 0xbfb8aa3b, v59
	v_exp_f32_e32 v49, v49
	v_exp_f32_e32 v50, v50
	v_exp_f32_e32 v51, v51
	v_exp_f32_e32 v53, v53
	v_pk_mul_f32 v[54:55], v[76:77], s[98:99] op_sel_hi:[1,0]
	v_mul_f32_e32 v65, 0xbfb8aa3b, v78
	v_mul_f32_e32 v84, 0xbfb8aa3b, v79
	v_exp_f32_e32 v54, v54
	v_exp_f32_e32 v55, v55
	v_exp_f32_e32 v65, v65
	v_exp_f32_e32 v84, v84
	v_add_f32_e32 v49, 1.0, v49
	v_pk_add_f32 v[50:51], v[50:51], 1.0 op_sel_hi:[1,0]
	v_add_f32_e32 v53, 1.0, v53
	v_rcp_f32_e32 v49, v49
	v_rcp_f32_e32 v50, v50
	v_rcp_f32_e32 v51, v51
	v_rcp_f32_e32 v53, v53
	v_lshl_add_u32 v48, s95, 7, v195
	v_pk_add_f32 v[54:55], v[54:55], 1.0 op_sel_hi:[1,0]
	v_add_f32_e32 v65, 1.0, v65
	v_add_f32_e32 v84, 1.0, v84
	v_ashrrev_i32_e32 v52, 10, v48
	v_rcp_f32_e32 v54, v54
	v_rcp_f32_e32 v55, v55
	v_rcp_f32_e32 v65, v65
	v_rcp_f32_e32 v84, v84
	v_and_b32_e32 v85, 0x3f8, v48
	v_cvt_pk_bf16_f32 v48, v49, v50
	v_cvt_pk_bf16_f32 v49, v51, v53
	v_ashrrev_i32_e32 v53, 31, v52
	v_lshlrev_b64 v[52:53], 25, v[52:53]
	v_lshl_add_u64 v[52:53], v[80:81], 0, v[52:53]
	v_lshlrev_b32_e32 v96, 1, v85
	v_cvt_pk_bf16_f32 v50, v54, v55
	v_cvt_pk_bf16_f32 v51, v65, v84
	v_lshl_add_u64 v[52:53], v[52:53], 0, v[96:97]
	s_mov_b64 s[14:15], 0
	global_store_dwordx4 v[52:53], v[48:51], off
	s_mov_b64 s[14:15], 0
	s_branch .LBB0_871

.LBB0_846:
	s_andn2_b64 vcc, exec, s[14:15]
	s_cbranch_vccnz .LBB0_848
	v_pk_mul_f32 v[48:49], v[56:57], s[98:99] op_sel_hi:[1,0]
	v_pk_mul_f32 v[50:51], v[58:59], s[98:99] op_sel_hi:[1,0]
	v_pk_mul_f32 v[52:53], v[76:77], s[98:99] op_sel_hi:[1,0]
	v_exp_f32_e32 v48, v48
	v_exp_f32_e32 v49, v49
	v_exp_f32_e32 v50, v50
	v_exp_f32_e32 v51, v51
	v_exp_f32_e32 v52, v52
	v_exp_f32_e32 v53, v53
	v_pk_mul_f32 v[54:55], v[78:79], s[98:99] op_sel_hi:[1,0]
	v_exp_f32_e32 v54, v54
	v_exp_f32_e32 v55, v55
	v_pk_add_f32 v[48:49], v[48:49], 1.0 op_sel_hi:[1,0]
	v_pk_add_f32 v[50:51], v[50:51], 1.0 op_sel_hi:[1,0]
	v_pk_add_f32 v[52:53], v[52:53], 1.0 op_sel_hi:[1,0]
	v_rcp_f32_e32 v48, v48
	v_rcp_f32_e32 v49, v49
	v_rcp_f32_e32 v50, v50
	v_rcp_f32_e32 v51, v51
	v_rcp_f32_e32 v52, v52
	v_rcp_f32_e32 v53, v53
	v_pk_add_f32 v[54:55], v[54:55], 1.0 op_sel_hi:[1,0]
	v_rcp_f32_e32 v54, v54
	v_rcp_f32_e32 v55, v55
	v_pk_mul_f32 v[48:49], v[56:57], v[48:49]
	v_pk_mul_f32 v[50:51], v[58:59], v[50:51]
	v_pk_mul_f32 v[52:53], v[76:77], v[52:53]
	s_lshl_b32 s48, s95, 8
	v_cvt_pk_bf16_f32 v48, v48, v49
	v_cvt_pk_bf16_f32 v49, v50, v51
	v_cvt_pk_bf16_f32 v50, v52, v53
	v_lshl_add_u64 v[52:53], v[66:67], 0, s[48:49]
	v_lshl_add_u64 v[52:53], v[146:147], 1, v[52:53]
	v_pk_mul_f32 v[54:55], v[78:79], v[54:55]
	v_add_co_u32_e32 v52, vcc, 0xd11e000, v52
	v_cvt_pk_bf16_f32 v51, v54, v55
	s_nop 0
	v_addc_co_u32_e32 v53, vcc, 0, v53, vcc
	global_store_dwordx4 v[52:53], v[48:51], off offset:3584
	s_mov_b64 s[14:15], 0
	s_branch .LBB0_871

.LBB0_855:
	s_andn2_b64 vcc, exec, s[14:15]
	s_cbranch_vccnz .LBB0_857
	v_pk_mul_f32 v[48:49], v[56:57], s[98:99] op_sel_hi:[1,0]
	v_pk_mul_f32 v[50:51], v[58:59], s[98:99] op_sel_hi:[1,0]
	v_pk_mul_f32 v[52:53], v[76:77], s[98:99] op_sel_hi:[1,0]
	v_exp_f32_e32 v48, v48
	v_exp_f32_e32 v49, v49
	v_exp_f32_e32 v50, v50
	v_exp_f32_e32 v51, v51
	v_exp_f32_e32 v52, v52
	v_exp_f32_e32 v53, v53
	v_pk_mul_f32 v[54:55], v[78:79], s[98:99] op_sel_hi:[1,0]
	v_exp_f32_e32 v54, v54
	v_exp_f32_e32 v55, v55
	v_pk_add_f32 v[48:49], v[48:49], 1.0 op_sel_hi:[1,0]
	v_pk_add_f32 v[50:51], v[50:51], 1.0 op_sel_hi:[1,0]
	v_pk_add_f32 v[52:53], v[52:53], 1.0 op_sel_hi:[1,0]
	v_rcp_f32_e32 v48, v48
	v_rcp_f32_e32 v49, v49
	v_rcp_f32_e32 v50, v50
	v_rcp_f32_e32 v51, v51
	v_rcp_f32_e32 v52, v52
	v_rcp_f32_e32 v53, v53
	v_pk_add_f32 v[54:55], v[54:55], 1.0 op_sel_hi:[1,0]
	v_rcp_f32_e32 v54, v54
	v_rcp_f32_e32 v55, v55
	v_pk_mul_f32 v[48:49], v[56:57], v[48:49]
	v_pk_mul_f32 v[50:51], v[58:59], v[50:51]
	v_pk_mul_f32 v[52:53], v[76:77], v[52:53]
	s_lshl_b32 s48, s95, 8
	v_cvt_pk_bf16_f32 v48, v48, v49
	v_cvt_pk_bf16_f32 v49, v50, v51
	v_cvt_pk_bf16_f32 v50, v52, v53
	v_lshl_add_u64 v[52:53], v[66:67], 0, s[48:49]
	v_lshl_add_u64 v[52:53], v[146:147], 1, v[52:53]
	v_pk_mul_f32 v[54:55], v[78:79], v[54:55]
	v_add_co_u32_e32 v52, vcc, 0x811f000, v52
	v_cvt_pk_bf16_f32 v51, v54, v55
	s_nop 0
	v_addc_co_u32_e32 v53, vcc, 0, v53, vcc
	global_store_dwordx4 v[52:53], v[48:51], off offset:2560
	s_mov_b64 s[14:15], 0
	s_branch .LBB0_871

.LBB0_871:
	v_add_f32_e32 v48, v200, v201
	v_fmamk_f32 v48, v48, 0x3a800000, v226
	v_rsq_f32_e32 v62, v48
	v_add_u32_e32 v48, 0x90, v148
	v_ashrrev_i32_e32 v49, 31, v48
	v_lshlrev_b64 v[52:53], 11, v[48:49]
	v_lshlrev_b64 v[56:57], 10, v[48:49]
	v_lshl_add_u64 v[64:65], s[50:51], 0, v[52:53]
	v_lshl_add_u64 v[50:51], s[72:73], 0, v[56:57]
	v_lshl_add_u64 v[54:55], s[52:53], 0, v[52:53]
	v_lshl_add_u64 v[52:53], s[96:97], 0, v[56:57]
	v_pk_mul_f32 v[60:61], v[44:45], v[62:63] op_sel_hi:[1,0]
	v_pk_mul_f32 v[68:69], v[46:47], v[62:63] op_sel_hi:[1,0]
	v_pk_mul_f32 v[70:71], v[40:41], v[62:63] op_sel_hi:[1,0]
	v_pk_mul_f32 v[72:73], v[42:43], v[62:63] op_sel_hi:[1,0]
	s_and_b64 vcc, exec, s[10:11]
	s_mov_b64 s[14:15], -1
	s_cbranch_vccnz .LBB0_893
	s_cmp_lt_u32 s94, 10
	s_cbranch_scc1 .LBB0_890
	s_cmp_lt_u32 s94, 14
	s_cbranch_scc1 .LBB0_887
	s_cmp_lt_u32 s94, 18
	s_cbranch_scc1 .LBB0_884
	s_cmp_lt_u32 s94, 22
	s_cbranch_scc1 .LBB0_881
	s_cmp_lt_u32 s94, 26
	s_cbranch_scc1 .LBB0_878
	v_mul_f32_e32 v41, 0xbfb8aa3b, v60
	v_mul_f32_e32 v42, 0xbfb8aa3b, v61
	v_mul_f32_e32 v43, 0xbfb8aa3b, v68
	v_mul_f32_e32 v45, 0xbfb8aa3b, v69
	v_exp_f32_e32 v41, v41
	v_exp_f32_e32 v42, v42
	v_exp_f32_e32 v43, v43
	v_exp_f32_e32 v45, v45
	v_pk_mul_f32 v[46:47], v[70:71], s[98:99] op_sel_hi:[1,0]
	v_pk_mul_f32 v[56:57], v[72:73], s[98:99] op_sel_hi:[1,0]
	v_exp_f32_e32 v46, v46
	v_exp_f32_e32 v47, v47
	v_exp_f32_e32 v56, v56
	v_exp_f32_e32 v57, v57
	v_add_f32_e32 v41, 1.0, v41
	v_pk_add_f32 v[42:43], v[42:43], 1.0 op_sel_hi:[1,0]
	v_add_f32_e32 v45, 1.0, v45
	v_rcp_f32_e32 v41, v41
	v_rcp_f32_e32 v42, v42
	v_rcp_f32_e32 v43, v43
	v_rcp_f32_e32 v45, v45
	v_lshl_add_u32 v40, s93, 8, v195
	v_pk_add_f32 v[46:47], v[46:47], 1.0 op_sel_hi:[1,0]
	v_pk_add_f32 v[56:57], v[56:57], 1.0 op_sel_hi:[1,0]
	v_ashrrev_i32_e32 v44, 10, v40
	v_rcp_f32_e32 v46, v46
	v_rcp_f32_e32 v47, v47
	v_rcp_f32_e32 v56, v56
	v_rcp_f32_e32 v57, v57
	v_and_b32_e32 v58, 0x3f8, v40
	v_cvt_pk_bf16_f32 v40, v41, v42
	v_cvt_pk_bf16_f32 v41, v43, v45
	v_ashrrev_i32_e32 v45, 31, v44
	v_lshlrev_b64 v[44:45], 25, v[44:45]
	v_lshl_add_u64 v[44:45], v[64:65], 0, v[44:45]
	v_lshlrev_b32_e32 v96, 1, v58
	v_cvt_pk_bf16_f32 v42, v46, v47
	v_cvt_pk_bf16_f32 v43, v56, v57
	v_lshl_add_u64 v[44:45], v[44:45], 0, v[96:97]
	s_mov_b64 s[14:15], 0
	global_store_dwordx4 v[44:45], v[40:43], off
	s_mov_b64 s[14:15], 0
	s_branch .LBB0_893

.LBB0_881:
	s_andn2_b64 vcc, exec, s[14:15]
	s_cbranch_vccnz .LBB0_883
	v_pk_mul_f32 v[40:41], v[60:61], s[98:99] op_sel_hi:[1,0]
	v_pk_mul_f32 v[42:43], v[68:69], s[98:99] op_sel_hi:[1,0]
	v_pk_mul_f32 v[44:45], v[70:71], s[98:99] op_sel_hi:[1,0]
	v_exp_f32_e32 v40, v40
	v_exp_f32_e32 v41, v41
	v_exp_f32_e32 v42, v42
	v_exp_f32_e32 v43, v43
	v_exp_f32_e32 v44, v44
	v_exp_f32_e32 v45, v45
	v_pk_mul_f32 v[46:47], v[72:73], s[98:99] op_sel_hi:[1,0]
	v_exp_f32_e32 v46, v46
	v_exp_f32_e32 v47, v47
	v_pk_add_f32 v[40:41], v[40:41], 1.0 op_sel_hi:[1,0]
	v_pk_add_f32 v[42:43], v[42:43], 1.0 op_sel_hi:[1,0]
	v_pk_add_f32 v[44:45], v[44:45], 1.0 op_sel_hi:[1,0]
	v_rcp_f32_e32 v40, v40
	v_rcp_f32_e32 v41, v41
	v_rcp_f32_e32 v42, v42
	v_rcp_f32_e32 v43, v43
	v_rcp_f32_e32 v44, v44
	v_rcp_f32_e32 v45, v45
	v_pk_add_f32 v[46:47], v[46:47], 1.0 op_sel_hi:[1,0]
	v_rcp_f32_e32 v46, v46
	v_rcp_f32_e32 v47, v47
	v_pk_mul_f32 v[40:41], v[60:61], v[40:41]
	v_pk_mul_f32 v[42:43], v[68:69], v[42:43]
	v_pk_mul_f32 v[44:45], v[70:71], v[44:45]
	s_lshl_b32 s48, s93, 8
	v_cvt_pk_bf16_f32 v40, v40, v41
	v_cvt_pk_bf16_f32 v41, v42, v43
	v_cvt_pk_bf16_f32 v42, v44, v45
	v_lshl_add_u64 v[44:45], s[48:49], 1, v[50:51]
	v_lshl_add_u64 v[44:45], v[146:147], 1, v[44:45]
	v_pk_mul_f32 v[46:47], v[72:73], v[46:47]
	v_add_co_u32_e32 v44, vcc, 0xd11e000, v44
	v_cvt_pk_bf16_f32 v43, v46, v47
	s_nop 0
	v_addc_co_u32_e32 v45, vcc, 0, v45, vcc
	global_store_dwordx4 v[44:45], v[40:43], off offset:3584
	s_mov_b64 s[14:15], 0
	s_branch .LBB0_893

.LBB0_890:
	s_andn2_b64 vcc, exec, s[14:15]
	s_cbranch_vccnz .LBB0_892
	v_pk_mul_f32 v[40:41], v[60:61], s[98:99] op_sel_hi:[1,0]
	v_pk_mul_f32 v[42:43], v[68:69], s[98:99] op_sel_hi:[1,0]
	v_pk_mul_f32 v[44:45], v[70:71], s[98:99] op_sel_hi:[1,0]
	v_exp_f32_e32 v40, v40
	v_exp_f32_e32 v41, v41
	v_exp_f32_e32 v42, v42
	v_exp_f32_e32 v43, v43
	v_exp_f32_e32 v44, v44
	v_exp_f32_e32 v45, v45
	v_pk_mul_f32 v[46:47], v[72:73], s[98:99] op_sel_hi:[1,0]
	v_exp_f32_e32 v46, v46
	v_exp_f32_e32 v47, v47
	v_pk_add_f32 v[40:41], v[40:41], 1.0 op_sel_hi:[1,0]
	v_pk_add_f32 v[42:43], v[42:43], 1.0 op_sel_hi:[1,0]
	v_pk_add_f32 v[44:45], v[44:45], 1.0 op_sel_hi:[1,0]
	v_rcp_f32_e32 v40, v40
	v_rcp_f32_e32 v41, v41
	v_rcp_f32_e32 v42, v42
	v_rcp_f32_e32 v43, v43
	v_rcp_f32_e32 v44, v44
	v_rcp_f32_e32 v45, v45
	v_pk_add_f32 v[46:47], v[46:47], 1.0 op_sel_hi:[1,0]
	v_rcp_f32_e32 v46, v46
	v_rcp_f32_e32 v47, v47
	v_pk_mul_f32 v[40:41], v[60:61], v[40:41]
	v_pk_mul_f32 v[42:43], v[68:69], v[42:43]
	v_pk_mul_f32 v[44:45], v[70:71], v[44:45]
	s_lshl_b32 s48, s93, 8
	v_cvt_pk_bf16_f32 v40, v40, v41
	v_cvt_pk_bf16_f32 v41, v42, v43
	v_cvt_pk_bf16_f32 v42, v44, v45
	v_lshl_add_u64 v[44:45], s[48:49], 1, v[50:51]
	v_lshl_add_u64 v[44:45], v[146:147], 1, v[44:45]
	v_pk_mul_f32 v[46:47], v[72:73], v[46:47]
	v_add_co_u32_e32 v44, vcc, 0x811f000, v44
	v_cvt_pk_bf16_f32 v43, v46, v47
	s_nop 0
	v_addc_co_u32_e32 v45, vcc, 0, v45, vcc
	global_store_dwordx4 v[44:45], v[40:43], off offset:2560

.LBB0_902:
	v_mov_b32_e32 v63, v62
	v_pk_mul_f32 v[40:41], v[36:37], v[62:63]
	v_pk_mul_f32 v[42:43], v[38:39], v[62:63]
	v_pk_mul_f32 v[60:61], v[32:33], v[62:63]
	v_pk_mul_f32 v[62:63], v[34:35], v[62:63]
	s_and_b64 vcc, exec, s[12:13]
	s_mov_b64 s[14:15], -1
	s_cbranch_vccnz .LBB0_929
	s_cmp_eq_u32 s93, 2
	s_cbranch_scc1 .LBB0_925
	s_cmp_lt_u32 s94, 10
	s_cbranch_scc1 .LBB0_922
	s_cmp_lt_u32 s94, 14
	s_cbranch_scc1 .LBB0_919
	s_cmp_lt_u32 s94, 18
	s_cbranch_scc1 .LBB0_916
	s_cmp_lt_u32 s94, 22
	s_cbranch_scc1 .LBB0_913
	s_cmp_lt_u32 s94, 26
	s_cbranch_scc1 .LBB0_910
	v_mul_f32_e32 v33, 0xbfb8aa3b, v40
	v_mul_f32_e32 v34, 0xbfb8aa3b, v41
	v_mul_f32_e32 v35, 0xbfb8aa3b, v42
	v_mul_f32_e32 v37, 0xbfb8aa3b, v43
	v_exp_f32_e32 v33, v33
	v_exp_f32_e32 v34, v34
	v_exp_f32_e32 v35, v35
	v_exp_f32_e32 v37, v37
	v_pk_mul_f32 v[38:39], v[60:61], s[98:99] op_sel_hi:[1,0]
	v_mul_f32_e32 v49, 0xbfb8aa3b, v62
	v_mul_f32_e32 v68, 0xbfb8aa3b, v63
	v_exp_f32_e32 v38, v38
	v_exp_f32_e32 v39, v39
	v_exp_f32_e32 v49, v49
	v_exp_f32_e32 v68, v68
	v_add_f32_e32 v33, 1.0, v33
	v_pk_add_f32 v[34:35], v[34:35], 1.0 op_sel_hi:[1,0]
	v_add_f32_e32 v37, 1.0, v37
	v_rcp_f32_e32 v33, v33
	v_rcp_f32_e32 v34, v34
	v_rcp_f32_e32 v35, v35
	v_rcp_f32_e32 v37, v37
	v_lshl_add_u32 v32, s95, 7, v195
	v_pk_add_f32 v[38:39], v[38:39], 1.0 op_sel_hi:[1,0]
	v_add_f32_e32 v49, 1.0, v49
	v_add_f32_e32 v68, 1.0, v68
	v_ashrrev_i32_e32 v36, 10, v32
	v_rcp_f32_e32 v38, v38
	v_rcp_f32_e32 v39, v39
	v_rcp_f32_e32 v49, v49
	v_rcp_f32_e32 v68, v68
	v_and_b32_e32 v69, 0x3f8, v32
	v_cvt_pk_bf16_f32 v32, v33, v34
	v_cvt_pk_bf16_f32 v33, v35, v37
	v_ashrrev_i32_e32 v37, 31, v36
	v_lshlrev_b64 v[36:37], 25, v[36:37]
	v_lshl_add_u64 v[36:37], v[64:65], 0, v[36:37]
	v_lshlrev_b32_e32 v96, 1, v69
	v_cvt_pk_bf16_f32 v34, v38, v39
	v_cvt_pk_bf16_f32 v35, v49, v68
	v_lshl_add_u64 v[36:37], v[36:37], 0, v[96:97]
	s_mov_b64 s[14:15], 0
	global_store_dwordx4 v[36:37], v[32:35], off
	s_mov_b64 s[14:15], 0
	s_branch .LBB0_938

.LBB0_913:
	s_andn2_b64 vcc, exec, s[14:15]
	s_cbranch_vccnz .LBB0_915
	v_pk_mul_f32 v[32:33], v[40:41], s[98:99] op_sel_hi:[1,0]
	v_pk_mul_f32 v[34:35], v[42:43], s[98:99] op_sel_hi:[1,0]
	v_pk_mul_f32 v[36:37], v[60:61], s[98:99] op_sel_hi:[1,0]
	v_exp_f32_e32 v32, v32
	v_exp_f32_e32 v33, v33
	v_exp_f32_e32 v34, v34
	v_exp_f32_e32 v35, v35
	v_exp_f32_e32 v36, v36
	v_exp_f32_e32 v37, v37
	v_pk_mul_f32 v[38:39], v[62:63], s[98:99] op_sel_hi:[1,0]
	v_exp_f32_e32 v38, v38
	v_exp_f32_e32 v39, v39
	v_pk_add_f32 v[32:33], v[32:33], 1.0 op_sel_hi:[1,0]
	v_pk_add_f32 v[34:35], v[34:35], 1.0 op_sel_hi:[1,0]
	v_pk_add_f32 v[36:37], v[36:37], 1.0 op_sel_hi:[1,0]
	v_rcp_f32_e32 v32, v32
	v_rcp_f32_e32 v33, v33
	v_rcp_f32_e32 v34, v34
	v_rcp_f32_e32 v35, v35
	v_rcp_f32_e32 v36, v36
	v_rcp_f32_e32 v37, v37
	v_pk_add_f32 v[38:39], v[38:39], 1.0 op_sel_hi:[1,0]
	v_rcp_f32_e32 v38, v38
	v_rcp_f32_e32 v39, v39
	v_pk_mul_f32 v[32:33], v[40:41], v[32:33]
	v_pk_mul_f32 v[34:35], v[42:43], v[34:35]
	v_pk_mul_f32 v[36:37], v[60:61], v[36:37]
	s_lshl_b32 s48, s95, 8
	v_cvt_pk_bf16_f32 v32, v32, v33
	v_cvt_pk_bf16_f32 v33, v34, v35
	v_cvt_pk_bf16_f32 v34, v36, v37
	v_lshl_add_u64 v[36:37], v[50:51], 0, s[48:49]
	v_lshl_add_u64 v[36:37], v[146:147], 1, v[36:37]
	v_pk_mul_f32 v[38:39], v[62:63], v[38:39]
	v_add_co_u32_e32 v36, vcc, 0xd11e000, v36
	v_cvt_pk_bf16_f32 v35, v38, v39
	s_nop 0
	v_addc_co_u32_e32 v37, vcc, 0, v37, vcc
	global_store_dwordx4 v[36:37], v[32:35], off offset:3584
	s_mov_b64 s[14:15], 0
	s_branch .LBB0_938

.LBB0_922:
	s_andn2_b64 vcc, exec, s[14:15]
	s_cbranch_vccnz .LBB0_924
	v_pk_mul_f32 v[32:33], v[40:41], s[98:99] op_sel_hi:[1,0]
	v_pk_mul_f32 v[34:35], v[42:43], s[98:99] op_sel_hi:[1,0]
	v_pk_mul_f32 v[36:37], v[60:61], s[98:99] op_sel_hi:[1,0]
	v_exp_f32_e32 v32, v32
	v_exp_f32_e32 v33, v33
	v_exp_f32_e32 v34, v34
	v_exp_f32_e32 v35, v35
	v_exp_f32_e32 v36, v36
	v_exp_f32_e32 v37, v37
	v_pk_mul_f32 v[38:39], v[62:63], s[98:99] op_sel_hi:[1,0]
	v_exp_f32_e32 v38, v38
	v_exp_f32_e32 v39, v39
	v_pk_add_f32 v[32:33], v[32:33], 1.0 op_sel_hi:[1,0]
	v_pk_add_f32 v[34:35], v[34:35], 1.0 op_sel_hi:[1,0]
	v_pk_add_f32 v[36:37], v[36:37], 1.0 op_sel_hi:[1,0]
	v_rcp_f32_e32 v32, v32
	v_rcp_f32_e32 v33, v33
	v_rcp_f32_e32 v34, v34
	v_rcp_f32_e32 v35, v35
	v_rcp_f32_e32 v36, v36
	v_rcp_f32_e32 v37, v37
	v_pk_add_f32 v[38:39], v[38:39], 1.0 op_sel_hi:[1,0]
	v_rcp_f32_e32 v38, v38
	v_rcp_f32_e32 v39, v39
	v_pk_mul_f32 v[32:33], v[40:41], v[32:33]
	v_pk_mul_f32 v[34:35], v[42:43], v[34:35]
	v_pk_mul_f32 v[36:37], v[60:61], v[36:37]
	s_lshl_b32 s48, s95, 8
	v_cvt_pk_bf16_f32 v32, v32, v33
	v_cvt_pk_bf16_f32 v33, v34, v35
	v_cvt_pk_bf16_f32 v34, v36, v37
	v_lshl_add_u64 v[36:37], v[50:51], 0, s[48:49]
	v_lshl_add_u64 v[36:37], v[146:147], 1, v[36:37]
	v_pk_mul_f32 v[38:39], v[62:63], v[38:39]
	v_add_co_u32_e32 v36, vcc, 0x811f000, v36
	v_cvt_pk_bf16_f32 v35, v38, v39
	s_nop 0
	v_addc_co_u32_e32 v37, vcc, 0, v37, vcc
	global_store_dwordx4 v[36:37], v[32:35], off offset:2560
	s_mov_b64 s[14:15], 0
	s_branch .LBB0_938

.LBB0_938:
	v_add_f32_e32 v32, v198, v199
	v_fmamk_f32 v32, v32, 0x3a800000, v226
	v_rsq_f32_e32 v46, v32
	v_add_u32_e32 v32, 0xa0, v148
	v_ashrrev_i32_e32 v33, 31, v32
	v_lshlrev_b64 v[36:37], 11, v[32:33]
	v_lshlrev_b64 v[40:41], 10, v[32:33]
	v_lshl_add_u64 v[48:49], s[50:51], 0, v[36:37]
	v_lshl_add_u64 v[34:35], s[72:73], 0, v[40:41]
	v_lshl_add_u64 v[38:39], s[52:53], 0, v[36:37]
	v_lshl_add_u64 v[36:37], s[96:97], 0, v[40:41]
	v_pk_mul_f32 v[44:45], v[28:29], v[46:47] op_sel_hi:[1,0]
	v_pk_mul_f32 v[52:53], v[30:31], v[46:47] op_sel_hi:[1,0]
	v_pk_mul_f32 v[54:55], v[24:25], v[46:47] op_sel_hi:[1,0]
	v_pk_mul_f32 v[56:57], v[26:27], v[46:47] op_sel_hi:[1,0]
	s_and_b64 vcc, exec, s[10:11]
	s_mov_b64 s[14:15], -1
	s_cbranch_vccnz .LBB0_960
	s_cmp_lt_u32 s94, 10
	s_cbranch_scc1 .LBB0_957
	s_cmp_lt_u32 s94, 14
	s_cbranch_scc1 .LBB0_954
	s_cmp_lt_u32 s94, 18
	s_cbranch_scc1 .LBB0_951
	s_cmp_lt_u32 s94, 22
	s_cbranch_scc1 .LBB0_948
	s_cmp_lt_u32 s94, 26
	s_cbranch_scc1 .LBB0_945
	v_mul_f32_e32 v25, 0xbfb8aa3b, v44
	v_mul_f32_e32 v26, 0xbfb8aa3b, v45
	v_mul_f32_e32 v27, 0xbfb8aa3b, v52
	v_mul_f32_e32 v29, 0xbfb8aa3b, v53
	v_exp_f32_e32 v25, v25
	v_exp_f32_e32 v26, v26
	v_exp_f32_e32 v27, v27
	v_exp_f32_e32 v29, v29
	v_pk_mul_f32 v[30:31], v[54:55], s[98:99] op_sel_hi:[1,0]
	v_pk_mul_f32 v[40:41], v[56:57], s[98:99] op_sel_hi:[1,0]
	v_exp_f32_e32 v30, v30
	v_exp_f32_e32 v31, v31
	v_exp_f32_e32 v40, v40
	v_exp_f32_e32 v41, v41
	v_add_f32_e32 v25, 1.0, v25
	v_pk_add_f32 v[26:27], v[26:27], 1.0 op_sel_hi:[1,0]
	v_add_f32_e32 v29, 1.0, v29
	v_rcp_f32_e32 v25, v25
	v_rcp_f32_e32 v26, v26
	v_rcp_f32_e32 v27, v27
	v_rcp_f32_e32 v29, v29
	v_lshl_add_u32 v24, s93, 8, v195
	v_pk_add_f32 v[30:31], v[30:31], 1.0 op_sel_hi:[1,0]
	v_pk_add_f32 v[40:41], v[40:41], 1.0 op_sel_hi:[1,0]
	v_ashrrev_i32_e32 v28, 10, v24
	v_rcp_f32_e32 v30, v30
	v_rcp_f32_e32 v31, v31
	v_rcp_f32_e32 v40, v40
	v_rcp_f32_e32 v41, v41
	v_and_b32_e32 v42, 0x3f8, v24
	v_cvt_pk_bf16_f32 v24, v25, v26
	v_cvt_pk_bf16_f32 v25, v27, v29
	v_ashrrev_i32_e32 v29, 31, v28
	v_lshlrev_b64 v[28:29], 25, v[28:29]
	v_lshl_add_u64 v[28:29], v[48:49], 0, v[28:29]
	v_lshlrev_b32_e32 v96, 1, v42
	v_cvt_pk_bf16_f32 v26, v30, v31
	v_cvt_pk_bf16_f32 v27, v40, v41
	v_lshl_add_u64 v[28:29], v[28:29], 0, v[96:97]
	s_mov_b64 s[14:15], 0
	global_store_dwordx4 v[28:29], v[24:27], off
	s_mov_b64 s[14:15], 0
	s_branch .LBB0_960

.LBB0_948:
	s_andn2_b64 vcc, exec, s[14:15]
	s_cbranch_vccnz .LBB0_950
	v_pk_mul_f32 v[24:25], v[44:45], s[98:99] op_sel_hi:[1,0]
	v_pk_mul_f32 v[26:27], v[52:53], s[98:99] op_sel_hi:[1,0]
	v_pk_mul_f32 v[28:29], v[54:55], s[98:99] op_sel_hi:[1,0]
	v_exp_f32_e32 v24, v24
	v_exp_f32_e32 v25, v25
	v_exp_f32_e32 v26, v26
	v_exp_f32_e32 v27, v27
	v_exp_f32_e32 v28, v28
	v_exp_f32_e32 v29, v29
	v_pk_mul_f32 v[30:31], v[56:57], s[98:99] op_sel_hi:[1,0]
	v_exp_f32_e32 v30, v30
	v_exp_f32_e32 v31, v31
	v_pk_add_f32 v[24:25], v[24:25], 1.0 op_sel_hi:[1,0]
	v_pk_add_f32 v[26:27], v[26:27], 1.0 op_sel_hi:[1,0]
	v_pk_add_f32 v[28:29], v[28:29], 1.0 op_sel_hi:[1,0]
	v_rcp_f32_e32 v24, v24
	v_rcp_f32_e32 v25, v25
	v_rcp_f32_e32 v26, v26
	v_rcp_f32_e32 v27, v27
	v_rcp_f32_e32 v28, v28
	v_rcp_f32_e32 v29, v29
	v_pk_add_f32 v[30:31], v[30:31], 1.0 op_sel_hi:[1,0]
	v_rcp_f32_e32 v30, v30
	v_rcp_f32_e32 v31, v31
	v_pk_mul_f32 v[24:25], v[44:45], v[24:25]
	v_pk_mul_f32 v[26:27], v[52:53], v[26:27]
	v_pk_mul_f32 v[28:29], v[54:55], v[28:29]
	s_lshl_b32 s48, s93, 8
	v_cvt_pk_bf16_f32 v24, v24, v25
	v_cvt_pk_bf16_f32 v25, v26, v27
	v_cvt_pk_bf16_f32 v26, v28, v29
	v_lshl_add_u64 v[28:29], s[48:49], 1, v[34:35]
	v_lshl_add_u64 v[28:29], v[146:147], 1, v[28:29]
	v_pk_mul_f32 v[30:31], v[56:57], v[30:31]
	v_add_co_u32_e32 v28, vcc, 0xd11e000, v28
	v_cvt_pk_bf16_f32 v27, v30, v31
	s_nop 0
	v_addc_co_u32_e32 v29, vcc, 0, v29, vcc
	global_store_dwordx4 v[28:29], v[24:27], off offset:3584
	s_mov_b64 s[14:15], 0
	s_branch .LBB0_960

.LBB0_957:
	s_andn2_b64 vcc, exec, s[14:15]
	s_cbranch_vccnz .LBB0_959
	v_pk_mul_f32 v[24:25], v[44:45], s[98:99] op_sel_hi:[1,0]
	v_pk_mul_f32 v[26:27], v[52:53], s[98:99] op_sel_hi:[1,0]
	v_pk_mul_f32 v[28:29], v[54:55], s[98:99] op_sel_hi:[1,0]
	v_exp_f32_e32 v24, v24
	v_exp_f32_e32 v25, v25
	v_exp_f32_e32 v26, v26
	v_exp_f32_e32 v27, v27
	v_exp_f32_e32 v28, v28
	v_exp_f32_e32 v29, v29
	v_pk_mul_f32 v[30:31], v[56:57], s[98:99] op_sel_hi:[1,0]
	v_exp_f32_e32 v30, v30
	v_exp_f32_e32 v31, v31
	v_pk_add_f32 v[24:25], v[24:25], 1.0 op_sel_hi:[1,0]
	v_pk_add_f32 v[26:27], v[26:27], 1.0 op_sel_hi:[1,0]
	v_pk_add_f32 v[28:29], v[28:29], 1.0 op_sel_hi:[1,0]
	v_rcp_f32_e32 v24, v24
	v_rcp_f32_e32 v25, v25
	v_rcp_f32_e32 v26, v26
	v_rcp_f32_e32 v27, v27
	v_rcp_f32_e32 v28, v28
	v_rcp_f32_e32 v29, v29
	v_pk_add_f32 v[30:31], v[30:31], 1.0 op_sel_hi:[1,0]
	v_rcp_f32_e32 v30, v30
	v_rcp_f32_e32 v31, v31
	v_pk_mul_f32 v[24:25], v[44:45], v[24:25]
	v_pk_mul_f32 v[26:27], v[52:53], v[26:27]
	v_pk_mul_f32 v[28:29], v[54:55], v[28:29]
	s_lshl_b32 s48, s93, 8
	v_cvt_pk_bf16_f32 v24, v24, v25
	v_cvt_pk_bf16_f32 v25, v26, v27
	v_cvt_pk_bf16_f32 v26, v28, v29
	v_lshl_add_u64 v[28:29], s[48:49], 1, v[34:35]
	v_lshl_add_u64 v[28:29], v[146:147], 1, v[28:29]
	v_pk_mul_f32 v[30:31], v[56:57], v[30:31]
	v_add_co_u32_e32 v28, vcc, 0x811f000, v28
	v_cvt_pk_bf16_f32 v27, v30, v31
	s_nop 0
	v_addc_co_u32_e32 v29, vcc, 0, v29, vcc
	global_store_dwordx4 v[28:29], v[24:27], off offset:2560

.LBB0_969:
	v_mov_b32_e32 v47, v46
	v_pk_mul_f32 v[24:25], v[20:21], v[46:47]
	v_pk_mul_f32 v[26:27], v[22:23], v[46:47]
	v_pk_mul_f32 v[44:45], v[16:17], v[46:47]
	v_pk_mul_f32 v[46:47], v[18:19], v[46:47]
	s_and_b64 vcc, exec, s[12:13]
	s_mov_b64 s[14:15], -1
	s_cbranch_vccnz .LBB0_996
	s_cmp_eq_u32 s93, 2
	s_cbranch_scc1 .LBB0_992
	s_cmp_lt_u32 s94, 10
	s_cbranch_scc1 .LBB0_989
	s_cmp_lt_u32 s94, 14
	s_cbranch_scc1 .LBB0_986
	s_cmp_lt_u32 s94, 18
	s_cbranch_scc1 .LBB0_983
	s_cmp_lt_u32 s94, 22
	s_cbranch_scc1 .LBB0_980
	s_cmp_lt_u32 s94, 26
	s_cbranch_scc1 .LBB0_977
	v_mul_f32_e32 v17, 0xbfb8aa3b, v24
	v_mul_f32_e32 v18, 0xbfb8aa3b, v25
	v_mul_f32_e32 v19, 0xbfb8aa3b, v26
	v_mul_f32_e32 v21, 0xbfb8aa3b, v27
	v_exp_f32_e32 v17, v17
	v_exp_f32_e32 v18, v18
	v_exp_f32_e32 v19, v19
	v_exp_f32_e32 v21, v21
	v_pk_mul_f32 v[22:23], v[44:45], s[98:99] op_sel_hi:[1,0]
	v_mul_f32_e32 v33, 0xbfb8aa3b, v46
	v_mul_f32_e32 v52, 0xbfb8aa3b, v47
	v_exp_f32_e32 v22, v22
	v_exp_f32_e32 v23, v23
	v_exp_f32_e32 v33, v33
	v_exp_f32_e32 v52, v52
	v_add_f32_e32 v17, 1.0, v17
	v_pk_add_f32 v[18:19], v[18:19], 1.0 op_sel_hi:[1,0]
	v_add_f32_e32 v21, 1.0, v21
	v_rcp_f32_e32 v17, v17
	v_rcp_f32_e32 v18, v18
	v_rcp_f32_e32 v19, v19
	v_rcp_f32_e32 v21, v21
	v_lshl_add_u32 v16, s95, 7, v195
	v_pk_add_f32 v[22:23], v[22:23], 1.0 op_sel_hi:[1,0]
	v_add_f32_e32 v33, 1.0, v33
	v_add_f32_e32 v52, 1.0, v52
	v_ashrrev_i32_e32 v20, 10, v16
	v_rcp_f32_e32 v22, v22
	v_rcp_f32_e32 v23, v23
	v_rcp_f32_e32 v33, v33
	v_rcp_f32_e32 v52, v52
	v_and_b32_e32 v53, 0x3f8, v16
	v_cvt_pk_bf16_f32 v16, v17, v18
	v_cvt_pk_bf16_f32 v17, v19, v21
	v_ashrrev_i32_e32 v21, 31, v20
	v_lshlrev_b64 v[20:21], 25, v[20:21]
	v_lshl_add_u64 v[20:21], v[48:49], 0, v[20:21]
	v_lshlrev_b32_e32 v96, 1, v53
	v_cvt_pk_bf16_f32 v18, v22, v23
	v_cvt_pk_bf16_f32 v19, v33, v52
	v_lshl_add_u64 v[20:21], v[20:21], 0, v[96:97]
	s_mov_b64 s[14:15], 0
	global_store_dwordx4 v[20:21], v[16:19], off
	s_mov_b64 s[14:15], 0
	s_branch .LBB0_1005

.LBB0_980:
	s_andn2_b64 vcc, exec, s[14:15]
	s_cbranch_vccnz .LBB0_982
	v_pk_mul_f32 v[16:17], v[24:25], s[98:99] op_sel_hi:[1,0]
	v_pk_mul_f32 v[18:19], v[26:27], s[98:99] op_sel_hi:[1,0]
	v_pk_mul_f32 v[20:21], v[44:45], s[98:99] op_sel_hi:[1,0]
	v_exp_f32_e32 v16, v16
	v_exp_f32_e32 v17, v17
	v_exp_f32_e32 v18, v18
	v_exp_f32_e32 v19, v19
	v_exp_f32_e32 v20, v20
	v_exp_f32_e32 v21, v21
	v_pk_mul_f32 v[22:23], v[46:47], s[98:99] op_sel_hi:[1,0]
	v_exp_f32_e32 v22, v22
	v_exp_f32_e32 v23, v23
	v_pk_add_f32 v[16:17], v[16:17], 1.0 op_sel_hi:[1,0]
	v_pk_add_f32 v[18:19], v[18:19], 1.0 op_sel_hi:[1,0]
	v_pk_add_f32 v[20:21], v[20:21], 1.0 op_sel_hi:[1,0]
	v_rcp_f32_e32 v16, v16
	v_rcp_f32_e32 v17, v17
	v_rcp_f32_e32 v18, v18
	v_rcp_f32_e32 v19, v19
	v_rcp_f32_e32 v20, v20
	v_rcp_f32_e32 v21, v21
	v_pk_add_f32 v[22:23], v[22:23], 1.0 op_sel_hi:[1,0]
	v_rcp_f32_e32 v22, v22
	v_rcp_f32_e32 v23, v23
	v_pk_mul_f32 v[16:17], v[24:25], v[16:17]
	v_pk_mul_f32 v[18:19], v[26:27], v[18:19]
	v_pk_mul_f32 v[20:21], v[44:45], v[20:21]
	s_lshl_b32 s48, s95, 8
	v_cvt_pk_bf16_f32 v16, v16, v17
	v_cvt_pk_bf16_f32 v17, v18, v19
	v_cvt_pk_bf16_f32 v18, v20, v21
	v_lshl_add_u64 v[20:21], v[34:35], 0, s[48:49]
	v_lshl_add_u64 v[20:21], v[146:147], 1, v[20:21]
	v_pk_mul_f32 v[22:23], v[46:47], v[22:23]
	v_add_co_u32_e32 v20, vcc, 0xd11e000, v20
	v_cvt_pk_bf16_f32 v19, v22, v23
	s_nop 0
	v_addc_co_u32_e32 v21, vcc, 0, v21, vcc
	global_store_dwordx4 v[20:21], v[16:19], off offset:3584
	s_mov_b64 s[14:15], 0
	s_branch .LBB0_1005

.LBB0_989:
	s_andn2_b64 vcc, exec, s[14:15]
	s_cbranch_vccnz .LBB0_991
	v_pk_mul_f32 v[16:17], v[24:25], s[98:99] op_sel_hi:[1,0]
	v_pk_mul_f32 v[18:19], v[26:27], s[98:99] op_sel_hi:[1,0]
	v_pk_mul_f32 v[20:21], v[44:45], s[98:99] op_sel_hi:[1,0]
	v_exp_f32_e32 v16, v16
	v_exp_f32_e32 v17, v17
	v_exp_f32_e32 v18, v18
	v_exp_f32_e32 v19, v19
	v_exp_f32_e32 v20, v20
	v_exp_f32_e32 v21, v21
	v_pk_mul_f32 v[22:23], v[46:47], s[98:99] op_sel_hi:[1,0]
	v_exp_f32_e32 v22, v22
	v_exp_f32_e32 v23, v23
	v_pk_add_f32 v[16:17], v[16:17], 1.0 op_sel_hi:[1,0]
	v_pk_add_f32 v[18:19], v[18:19], 1.0 op_sel_hi:[1,0]
	v_pk_add_f32 v[20:21], v[20:21], 1.0 op_sel_hi:[1,0]
	v_rcp_f32_e32 v16, v16
	v_rcp_f32_e32 v17, v17
	v_rcp_f32_e32 v18, v18
	v_rcp_f32_e32 v19, v19
	v_rcp_f32_e32 v20, v20
	v_rcp_f32_e32 v21, v21
	v_pk_add_f32 v[22:23], v[22:23], 1.0 op_sel_hi:[1,0]
	v_rcp_f32_e32 v22, v22
	v_rcp_f32_e32 v23, v23
	v_pk_mul_f32 v[16:17], v[24:25], v[16:17]
	v_pk_mul_f32 v[18:19], v[26:27], v[18:19]
	v_pk_mul_f32 v[20:21], v[44:45], v[20:21]
	s_lshl_b32 s48, s95, 8
	v_cvt_pk_bf16_f32 v16, v16, v17
	v_cvt_pk_bf16_f32 v17, v18, v19
	v_cvt_pk_bf16_f32 v18, v20, v21
	v_lshl_add_u64 v[20:21], v[34:35], 0, s[48:49]
	v_lshl_add_u64 v[20:21], v[146:147], 1, v[20:21]
	v_pk_mul_f32 v[22:23], v[46:47], v[22:23]
	v_add_co_u32_e32 v20, vcc, 0x811f000, v20
	v_cvt_pk_bf16_f32 v19, v22, v23
	s_nop 0
	v_addc_co_u32_e32 v21, vcc, 0, v21, vcc
	global_store_dwordx4 v[20:21], v[16:19], off offset:2560
	s_mov_b64 s[14:15], 0
	s_branch .LBB0_1005

.LBB0_1005:
	v_add_f32_e32 v16, v196, v197
	v_fmamk_f32 v16, v16, 0x3a800000, v226
	v_rsq_f32_e32 v30, v16
	v_add_u32_e32 v16, 0xb0, v148
	v_ashrrev_i32_e32 v17, 31, v16
	v_lshlrev_b64 v[20:21], 11, v[16:17]
	v_lshlrev_b64 v[24:25], 10, v[16:17]
	v_lshl_add_u64 v[32:33], s[50:51], 0, v[20:21]
	v_lshl_add_u64 v[18:19], s[72:73], 0, v[24:25]
	v_lshl_add_u64 v[22:23], s[52:53], 0, v[20:21]
	v_lshl_add_u64 v[20:21], s[96:97], 0, v[24:25]
	v_pk_mul_f32 v[28:29], v[12:13], v[30:31] op_sel_hi:[1,0]
	v_pk_mul_f32 v[36:37], v[14:15], v[30:31] op_sel_hi:[1,0]
	v_pk_mul_f32 v[38:39], v[8:9], v[30:31] op_sel_hi:[1,0]
	v_pk_mul_f32 v[40:41], v[10:11], v[30:31] op_sel_hi:[1,0]
	s_and_b64 vcc, exec, s[10:11]
	s_mov_b64 s[10:11], -1
	s_cbranch_vccnz .LBB0_1027
	s_cmp_lt_u32 s94, 10
	s_cbranch_scc1 .LBB0_1024
	s_cmp_lt_u32 s94, 14
	s_cbranch_scc1 .LBB0_1021
	s_cmp_lt_u32 s94, 18
	s_cbranch_scc1 .LBB0_1018
	s_cmp_lt_u32 s94, 22
	s_cbranch_scc1 .LBB0_1015
	s_cmp_lt_u32 s94, 26
	s_cbranch_scc1 .LBB0_1012
	v_mul_f32_e32 v9, 0xbfb8aa3b, v28
	v_mul_f32_e32 v10, 0xbfb8aa3b, v29
	v_mul_f32_e32 v11, 0xbfb8aa3b, v36
	v_mul_f32_e32 v13, 0xbfb8aa3b, v37
	v_exp_f32_e32 v9, v9
	v_exp_f32_e32 v10, v10
	v_exp_f32_e32 v11, v11
	v_exp_f32_e32 v13, v13
	v_pk_mul_f32 v[14:15], v[38:39], s[98:99] op_sel_hi:[1,0]
	v_pk_mul_f32 v[24:25], v[40:41], s[98:99] op_sel_hi:[1,0]
	v_exp_f32_e32 v14, v14
	v_exp_f32_e32 v15, v15
	v_exp_f32_e32 v24, v24
	v_exp_f32_e32 v25, v25
	v_add_f32_e32 v9, 1.0, v9
	v_pk_add_f32 v[10:11], v[10:11], 1.0 op_sel_hi:[1,0]
	v_add_f32_e32 v13, 1.0, v13
	v_rcp_f32_e32 v9, v9
	v_rcp_f32_e32 v10, v10
	v_rcp_f32_e32 v11, v11
	v_rcp_f32_e32 v13, v13
	v_lshl_add_u32 v8, s93, 8, v195
	v_pk_add_f32 v[14:15], v[14:15], 1.0 op_sel_hi:[1,0]
	v_pk_add_f32 v[24:25], v[24:25], 1.0 op_sel_hi:[1,0]
	v_ashrrev_i32_e32 v12, 10, v8
	v_rcp_f32_e32 v14, v14
	v_rcp_f32_e32 v15, v15
	v_rcp_f32_e32 v24, v24
	v_rcp_f32_e32 v25, v25
	v_and_b32_e32 v26, 0x3f8, v8
	v_cvt_pk_bf16_f32 v8, v9, v10
	v_cvt_pk_bf16_f32 v9, v11, v13
	v_ashrrev_i32_e32 v13, 31, v12
	v_lshlrev_b64 v[12:13], 25, v[12:13]
	v_lshl_add_u64 v[12:13], v[32:33], 0, v[12:13]
	v_lshlrev_b32_e32 v96, 1, v26
	v_cvt_pk_bf16_f32 v10, v14, v15
	v_cvt_pk_bf16_f32 v11, v24, v25
	v_lshl_add_u64 v[12:13], v[12:13], 0, v[96:97]
	s_mov_b64 s[10:11], 0
	global_store_dwordx4 v[12:13], v[8:11], off
	s_mov_b64 s[10:11], 0
	s_branch .LBB0_1027

.LBB0_1015:
	s_andn2_b64 vcc, exec, s[10:11]
	s_cbranch_vccnz .LBB0_1017
	v_pk_mul_f32 v[8:9], v[28:29], s[98:99] op_sel_hi:[1,0]
	v_pk_mul_f32 v[10:11], v[36:37], s[98:99] op_sel_hi:[1,0]
	v_pk_mul_f32 v[12:13], v[38:39], s[98:99] op_sel_hi:[1,0]
	v_exp_f32_e32 v8, v8
	v_exp_f32_e32 v9, v9
	v_exp_f32_e32 v10, v10
	v_exp_f32_e32 v11, v11
	v_exp_f32_e32 v12, v12
	v_exp_f32_e32 v13, v13
	v_pk_mul_f32 v[14:15], v[40:41], s[98:99] op_sel_hi:[1,0]
	v_exp_f32_e32 v14, v14
	v_exp_f32_e32 v15, v15
	v_pk_add_f32 v[8:9], v[8:9], 1.0 op_sel_hi:[1,0]
	v_pk_add_f32 v[10:11], v[10:11], 1.0 op_sel_hi:[1,0]
	v_pk_add_f32 v[12:13], v[12:13], 1.0 op_sel_hi:[1,0]
	v_rcp_f32_e32 v8, v8
	v_rcp_f32_e32 v9, v9
	v_rcp_f32_e32 v10, v10
	v_rcp_f32_e32 v11, v11
	v_rcp_f32_e32 v12, v12
	v_rcp_f32_e32 v13, v13
	v_pk_add_f32 v[14:15], v[14:15], 1.0 op_sel_hi:[1,0]
	v_rcp_f32_e32 v14, v14
	v_rcp_f32_e32 v15, v15
	v_pk_mul_f32 v[8:9], v[28:29], v[8:9]
	v_pk_mul_f32 v[10:11], v[36:37], v[10:11]
	v_pk_mul_f32 v[12:13], v[38:39], v[12:13]
	s_lshl_b32 s48, s93, 8
	v_cvt_pk_bf16_f32 v8, v8, v9
	v_cvt_pk_bf16_f32 v9, v10, v11
	v_cvt_pk_bf16_f32 v10, v12, v13
	v_lshl_add_u64 v[12:13], s[48:49], 1, v[18:19]
	v_lshl_add_u64 v[12:13], v[146:147], 1, v[12:13]
	v_pk_mul_f32 v[14:15], v[40:41], v[14:15]
	v_add_co_u32_e32 v12, vcc, 0xd11e000, v12
	v_cvt_pk_bf16_f32 v11, v14, v15
	s_nop 0
	v_addc_co_u32_e32 v13, vcc, 0, v13, vcc
	global_store_dwordx4 v[12:13], v[8:11], off offset:3584
	s_mov_b64 s[10:11], 0
	s_branch .LBB0_1027

.LBB0_1024:
	s_andn2_b64 vcc, exec, s[10:11]
	s_cbranch_vccnz .LBB0_1026
	v_pk_mul_f32 v[8:9], v[28:29], s[98:99] op_sel_hi:[1,0]
	v_pk_mul_f32 v[10:11], v[36:37], s[98:99] op_sel_hi:[1,0]
	v_pk_mul_f32 v[12:13], v[38:39], s[98:99] op_sel_hi:[1,0]
	v_exp_f32_e32 v8, v8
	v_exp_f32_e32 v9, v9
	v_exp_f32_e32 v10, v10
	v_exp_f32_e32 v11, v11
	v_exp_f32_e32 v12, v12
	v_exp_f32_e32 v13, v13
	v_pk_mul_f32 v[14:15], v[40:41], s[98:99] op_sel_hi:[1,0]
	v_exp_f32_e32 v14, v14
	v_exp_f32_e32 v15, v15
	v_pk_add_f32 v[8:9], v[8:9], 1.0 op_sel_hi:[1,0]
	v_pk_add_f32 v[10:11], v[10:11], 1.0 op_sel_hi:[1,0]
	v_pk_add_f32 v[12:13], v[12:13], 1.0 op_sel_hi:[1,0]
	v_rcp_f32_e32 v8, v8
	v_rcp_f32_e32 v9, v9
	v_rcp_f32_e32 v10, v10
	v_rcp_f32_e32 v11, v11
	v_rcp_f32_e32 v12, v12
	v_rcp_f32_e32 v13, v13
	v_pk_add_f32 v[14:15], v[14:15], 1.0 op_sel_hi:[1,0]
	v_rcp_f32_e32 v14, v14
	v_rcp_f32_e32 v15, v15
	v_pk_mul_f32 v[8:9], v[28:29], v[8:9]
	v_pk_mul_f32 v[10:11], v[36:37], v[10:11]
	v_pk_mul_f32 v[12:13], v[38:39], v[12:13]
	s_lshl_b32 s48, s93, 8
	v_cvt_pk_bf16_f32 v8, v8, v9
	v_cvt_pk_bf16_f32 v9, v10, v11
	v_cvt_pk_bf16_f32 v10, v12, v13
	v_lshl_add_u64 v[12:13], s[48:49], 1, v[18:19]
	v_lshl_add_u64 v[12:13], v[146:147], 1, v[12:13]
	v_pk_mul_f32 v[14:15], v[40:41], v[14:15]
	v_add_co_u32_e32 v12, vcc, 0x811f000, v12
	v_cvt_pk_bf16_f32 v11, v14, v15
	s_nop 0
	v_addc_co_u32_e32 v13, vcc, 0, v13, vcc
	global_store_dwordx4 v[12:13], v[8:11], off offset:2560

.LBB0_1036:
	v_mov_b32_e32 v31, v30
	v_pk_mul_f32 v[8:9], v[4:5], v[30:31]
	v_pk_mul_f32 v[10:11], v[6:7], v[30:31]
	v_pk_mul_f32 v[28:29], v[0:1], v[30:31]
	v_pk_mul_f32 v[30:31], v[2:3], v[30:31]
	s_and_b64 vcc, exec, s[12:13]
	s_mov_b64 s[10:11], -1
	s_cbranch_vccnz .LBB0_1063
	s_cmp_eq_u32 s93, 2
	s_cbranch_scc1 .LBB0_1059
	s_cmp_lt_u32 s94, 10
	s_cbranch_scc1 .LBB0_1056
	s_cmp_lt_u32 s94, 14
	s_cbranch_scc1 .LBB0_1053
	s_cmp_lt_u32 s94, 18
	s_cbranch_scc1 .LBB0_1050
	s_cmp_lt_u32 s94, 22
	s_cbranch_scc1 .LBB0_1047
	s_cmp_lt_u32 s94, 26
	s_cbranch_scc1 .LBB0_1044
	v_mul_f32_e32 v1, 0xbfb8aa3b, v8
	v_mul_f32_e32 v2, 0xbfb8aa3b, v9
	v_mul_f32_e32 v3, 0xbfb8aa3b, v10
	v_mul_f32_e32 v5, 0xbfb8aa3b, v11
	v_exp_f32_e32 v1, v1
	v_exp_f32_e32 v2, v2
	v_exp_f32_e32 v3, v3
	v_exp_f32_e32 v5, v5
	v_pk_mul_f32 v[6:7], v[28:29], s[98:99] op_sel_hi:[1,0]
	v_mul_f32_e32 v17, 0xbfb8aa3b, v30
	v_mul_f32_e32 v36, 0xbfb8aa3b, v31
	v_exp_f32_e32 v6, v6
	v_exp_f32_e32 v7, v7
	v_exp_f32_e32 v17, v17
	v_exp_f32_e32 v36, v36
	v_add_f32_e32 v1, 1.0, v1
	v_pk_add_f32 v[2:3], v[2:3], 1.0 op_sel_hi:[1,0]
	v_add_f32_e32 v5, 1.0, v5
	v_rcp_f32_e32 v1, v1
	v_rcp_f32_e32 v2, v2
	v_rcp_f32_e32 v3, v3
	v_rcp_f32_e32 v5, v5
	v_lshl_add_u32 v0, s95, 7, v195
	v_pk_add_f32 v[6:7], v[6:7], 1.0 op_sel_hi:[1,0]
	v_add_f32_e32 v17, 1.0, v17
	v_add_f32_e32 v36, 1.0, v36
	v_ashrrev_i32_e32 v4, 10, v0
	v_rcp_f32_e32 v6, v6
	v_rcp_f32_e32 v7, v7
	v_rcp_f32_e32 v17, v17
	v_rcp_f32_e32 v36, v36
	v_and_b32_e32 v37, 0x3f8, v0
	v_cvt_pk_bf16_f32 v0, v1, v2
	v_cvt_pk_bf16_f32 v1, v3, v5
	v_ashrrev_i32_e32 v5, 31, v4
	v_lshlrev_b64 v[4:5], 25, v[4:5]
	v_lshl_add_u64 v[4:5], v[32:33], 0, v[4:5]
	v_lshlrev_b32_e32 v96, 1, v37
	v_cvt_pk_bf16_f32 v2, v6, v7
	v_cvt_pk_bf16_f32 v3, v17, v36
	v_lshl_add_u64 v[4:5], v[4:5], 0, v[96:97]
	s_mov_b64 s[10:11], 0
	global_store_dwordx4 v[4:5], v[0:3], off
	s_mov_b64 s[10:11], 0
	s_branch .LBB0_1072

.LBB0_1047:
	s_andn2_b64 vcc, exec, s[10:11]
	s_cbranch_vccnz .LBB0_1049
	v_pk_mul_f32 v[0:1], v[8:9], s[98:99] op_sel_hi:[1,0]
	v_pk_mul_f32 v[2:3], v[10:11], s[98:99] op_sel_hi:[1,0]
	v_pk_mul_f32 v[4:5], v[28:29], s[98:99] op_sel_hi:[1,0]
	v_exp_f32_e32 v0, v0
	v_exp_f32_e32 v1, v1
	v_exp_f32_e32 v2, v2
	v_exp_f32_e32 v3, v3
	v_exp_f32_e32 v4, v4
	v_exp_f32_e32 v5, v5
	v_pk_mul_f32 v[6:7], v[30:31], s[98:99] op_sel_hi:[1,0]
	v_exp_f32_e32 v6, v6
	v_exp_f32_e32 v7, v7
	v_pk_add_f32 v[0:1], v[0:1], 1.0 op_sel_hi:[1,0]
	v_pk_add_f32 v[2:3], v[2:3], 1.0 op_sel_hi:[1,0]
	v_pk_add_f32 v[4:5], v[4:5], 1.0 op_sel_hi:[1,0]
	v_rcp_f32_e32 v0, v0
	v_rcp_f32_e32 v1, v1
	v_rcp_f32_e32 v2, v2
	v_rcp_f32_e32 v3, v3
	v_rcp_f32_e32 v4, v4
	v_rcp_f32_e32 v5, v5
	v_pk_add_f32 v[6:7], v[6:7], 1.0 op_sel_hi:[1,0]
	v_rcp_f32_e32 v6, v6
	v_rcp_f32_e32 v7, v7
	v_pk_mul_f32 v[0:1], v[8:9], v[0:1]
	v_pk_mul_f32 v[2:3], v[10:11], v[2:3]
	v_pk_mul_f32 v[4:5], v[28:29], v[4:5]
	s_lshl_b32 s48, s95, 8
	v_cvt_pk_bf16_f32 v0, v0, v1
	v_cvt_pk_bf16_f32 v1, v2, v3
	v_cvt_pk_bf16_f32 v2, v4, v5
	v_lshl_add_u64 v[4:5], v[18:19], 0, s[48:49]
	v_lshl_add_u64 v[4:5], v[146:147], 1, v[4:5]
	v_pk_mul_f32 v[6:7], v[30:31], v[6:7]
	v_add_co_u32_e32 v4, vcc, 0xd11e000, v4
	v_cvt_pk_bf16_f32 v3, v6, v7
	s_nop 0
	v_addc_co_u32_e32 v5, vcc, 0, v5, vcc
	global_store_dwordx4 v[4:5], v[0:3], off offset:3584
	s_mov_b64 s[10:11], 0
	s_branch .LBB0_1072

.LBB0_1056:
	s_andn2_b64 vcc, exec, s[10:11]
	s_cbranch_vccnz .LBB0_1058
	v_pk_mul_f32 v[0:1], v[8:9], s[98:99] op_sel_hi:[1,0]
	v_pk_mul_f32 v[2:3], v[10:11], s[98:99] op_sel_hi:[1,0]
	v_pk_mul_f32 v[4:5], v[28:29], s[98:99] op_sel_hi:[1,0]
	v_exp_f32_e32 v0, v0
	v_exp_f32_e32 v1, v1
	v_exp_f32_e32 v2, v2
	v_exp_f32_e32 v3, v3
	v_exp_f32_e32 v4, v4
	v_exp_f32_e32 v5, v5
	v_pk_mul_f32 v[6:7], v[30:31], s[98:99] op_sel_hi:[1,0]
	v_exp_f32_e32 v6, v6
	v_exp_f32_e32 v7, v7
	v_pk_add_f32 v[0:1], v[0:1], 1.0 op_sel_hi:[1,0]
	v_pk_add_f32 v[2:3], v[2:3], 1.0 op_sel_hi:[1,0]
	v_pk_add_f32 v[4:5], v[4:5], 1.0 op_sel_hi:[1,0]
	v_rcp_f32_e32 v0, v0
	v_rcp_f32_e32 v1, v1
	v_rcp_f32_e32 v2, v2
	v_rcp_f32_e32 v3, v3
	v_rcp_f32_e32 v4, v4
	v_rcp_f32_e32 v5, v5
	v_pk_add_f32 v[6:7], v[6:7], 1.0 op_sel_hi:[1,0]
	v_rcp_f32_e32 v6, v6
	v_rcp_f32_e32 v7, v7
	v_pk_mul_f32 v[0:1], v[8:9], v[0:1]
	v_pk_mul_f32 v[2:3], v[10:11], v[2:3]
	v_pk_mul_f32 v[4:5], v[28:29], v[4:5]
	s_lshl_b32 s48, s95, 8
	v_cvt_pk_bf16_f32 v0, v0, v1
	v_cvt_pk_bf16_f32 v1, v2, v3
	v_cvt_pk_bf16_f32 v2, v4, v5
	v_lshl_add_u64 v[4:5], v[18:19], 0, s[48:49]
	v_lshl_add_u64 v[4:5], v[146:147], 1, v[4:5]
	v_pk_mul_f32 v[6:7], v[30:31], v[6:7]
	v_add_co_u32_e32 v4, vcc, 0x811f000, v4
	v_cvt_pk_bf16_f32 v3, v6, v7
	s_nop 0
	v_addc_co_u32_e32 v5, vcc, 0, v5, vcc
	global_store_dwordx4 v[4:5], v[0:3], off offset:2560
	s_mov_b64 s[10:11], 0
	s_branch .LBB0_1072
